# GEMM K-loops: one s_setprio 1 per phase (no dip between the two MFMA clusters) and the provably redundant in-cluster lgkmcnt waits deleted
# speedup vs baseline: 1.0083x; 1.0083x over previous
.LBB0_95:
	v_add_u32_e32 v0, 0x10000, v134
	ds_read_b128 v[136:139], v0
	ds_read_b128 v[140:143], v0 offset:1024
	ds_read_b128 v[144:147], v0 offset:2048
	ds_read_b128 v[148:151], v0 offset:3072
	v_add_u32_e32 v0, 0x14000, v134
	ds_read_b128 v[152:155], v0
	ds_read_b128 v[156:159], v0 offset:1024
	ds_read_b128 v[160:163], v0 offset:2048
	ds_read_b128 v[164:167], v0 offset:3072
	s_cmp_eq_u32 s51, 12
	s_cselect_b32 s56, s48, s26
	s_cselect_b32 s57, s49, s27
	s_cselect_b32 s54, s40, s24
	s_cselect_b32 s55, s41, s25
	s_add_u32 s52, s56, 0x80
	s_addc_u32 s53, s57, 0
	ds_read_b128 v[168:171], v135
	ds_read_b128 v[172:175], v135 offset:1024
	ds_read_b128 v[176:179], v135 offset:2048
	ds_read_b128 v[180:183], v135 offset:3072
	ds_read_b128 v[184:187], v135 offset:4096
	ds_read_b128 v[188:191], v135 offset:5120
	ds_read_b128 v[192:195], v135 offset:6144
	ds_read_b128 v[196:199], v135 offset:7168
	s_add_u32 s58, s26, s4
	s_addc_u32 s59, s27, s5
	s_add_u32 s58, s58, 0xffffff80
	s_addc_u32 s59, s59, -1
	s_mov_b32 s76, m0
	s_mov_b32 m0, s71
	s_nop 0
	global_load_lds_dwordx4 v130, s[58:59]
	s_mov_b32 m0, s72
	s_nop 0
	global_load_lds_dwordx4 v132, s[58:59]
	s_mov_b32 m0, s76
	s_waitcnt vmcnt(8)
	s_waitcnt lgkmcnt(0)
	s_barrier
	s_setprio 1
	v_mfma_f32_16x16x32_bf16 v[126:129], v[136:139], v[168:171], v[126:129]
	v_mfma_f32_16x16x32_bf16 v[122:125], v[144:147], v[168:171], v[122:125]
	v_mfma_f32_16x16x32_bf16 v[110:113], v[136:139], v[176:179], v[110:113]
	v_mfma_f32_16x16x32_bf16 v[106:109], v[144:147], v[176:179], v[106:109]
	v_mfma_f32_16x16x32_bf16 v[94:97], v[136:139], v[184:187], v[94:97]
	v_mfma_f32_16x16x32_bf16 v[90:93], v[144:147], v[184:187], v[90:93]
	v_mfma_f32_16x16x32_bf16 v[78:81], v[136:139], v[192:195], v[78:81]
	v_mfma_f32_16x16x32_bf16 v[74:77], v[144:147], v[192:195], v[74:77]
	v_mfma_f32_16x16x32_bf16 v[126:129], v[140:143], v[172:175], v[126:129]
	v_mfma_f32_16x16x32_bf16 v[122:125], v[148:151], v[172:175], v[122:125]
	v_mfma_f32_16x16x32_bf16 v[110:113], v[140:143], v[180:183], v[110:113]
	v_mfma_f32_16x16x32_bf16 v[106:109], v[148:151], v[180:183], v[106:109]
	v_mfma_f32_16x16x32_bf16 v[94:97], v[140:143], v[188:191], v[94:97]
	v_mfma_f32_16x16x32_bf16 v[90:93], v[148:151], v[188:191], v[90:93]
	v_mfma_f32_16x16x32_bf16 v[78:81], v[140:143], v[196:199], v[78:81]
	v_mfma_f32_16x16x32_bf16 v[74:77], v[148:151], v[196:199], v[74:77]
	v_mfma_f32_16x16x32_bf16 v[118:121], v[152:155], v[168:171], v[118:121]
	v_mfma_f32_16x16x32_bf16 v[114:117], v[160:163], v[168:171], v[114:117]
	v_mfma_f32_16x16x32_bf16 v[102:105], v[152:155], v[176:179], v[102:105]
	v_mfma_f32_16x16x32_bf16 v[98:101], v[160:163], v[176:179], v[98:101]
	v_mfma_f32_16x16x32_bf16 v[86:89], v[152:155], v[184:187], v[86:89]
	v_mfma_f32_16x16x32_bf16 v[82:85], v[160:163], v[184:187], v[82:85]
	v_mfma_f32_16x16x32_bf16 v[70:73], v[152:155], v[192:195], v[70:73]
	v_mfma_f32_16x16x32_bf16 v[66:69], v[160:163], v[192:195], v[66:69]
	v_mfma_f32_16x16x32_bf16 v[118:121], v[156:159], v[172:175], v[118:121]
	v_mfma_f32_16x16x32_bf16 v[114:117], v[164:167], v[172:175], v[114:117]
	v_mfma_f32_16x16x32_bf16 v[102:105], v[156:159], v[180:183], v[102:105]
	v_mfma_f32_16x16x32_bf16 v[98:101], v[164:167], v[180:183], v[98:101]
	v_mfma_f32_16x16x32_bf16 v[86:89], v[156:159], v[188:191], v[86:89]
	v_mfma_f32_16x16x32_bf16 v[82:85], v[164:167], v[188:191], v[82:85]
	v_mfma_f32_16x16x32_bf16 v[70:73], v[156:159], v[196:199], v[70:73]
	v_mfma_f32_16x16x32_bf16 v[66:69], v[164:167], v[196:199], v[66:69]
	s_setprio 0
	s_barrier
	ds_read_b128 v[168:171], v135 offset:16384
	ds_read_b128 v[172:175], v135 offset:17408
	ds_read_b128 v[176:179], v135 offset:18432
	ds_read_b128 v[180:183], v135 offset:19456
	ds_read_b128 v[184:187], v135 offset:20480
	ds_read_b128 v[188:191], v135 offset:21504
	ds_read_b128 v[192:195], v135 offset:22528
	ds_read_b128 v[196:199], v135 offset:23552
	s_mov_b32 s58, m0
	s_mov_b32 m0, s28
	s_nop 0
	global_load_lds_dwordx4 v131, s[54:55]
	s_mov_b32 m0, s29
	s_nop 0
	global_load_lds_dwordx4 v133, s[54:55]
	s_mov_b32 m0, s58
	s_add_u32 s58, s54, s20
	s_addc_u32 s59, s55, s21
	s_mov_b32 s76, m0
	s_mov_b32 m0, s30
	s_nop 0
	global_load_lds_dwordx4 v131, s[58:59]
	s_mov_b32 m0, s31
	s_nop 0
	global_load_lds_dwordx4 v133, s[58:59]
	s_mov_b32 m0, s76
	s_nop 0
	s_mov_b32 s76, m0
	s_mov_b32 m0, s11
	s_nop 0
	global_load_lds_dwordx4 v130, s[56:57]
	s_mov_b32 m0, s60
	s_nop 0
	global_load_lds_dwordx4 v132, s[56:57]
	s_mov_b32 m0, s76
	s_waitcnt vmcnt(8)
	s_waitcnt lgkmcnt(0)
	s_barrier
	s_setprio 1
	v_mfma_f32_16x16x32_bf16 v[62:65], v[136:139], v[168:171], v[62:65]
	v_mfma_f32_16x16x32_bf16 v[58:61], v[144:147], v[168:171], v[58:61]
	v_mfma_f32_16x16x32_bf16 v[46:49], v[136:139], v[176:179], v[46:49]
	v_mfma_f32_16x16x32_bf16 v[42:45], v[144:147], v[176:179], v[42:45]
	v_mfma_f32_16x16x32_bf16 v[30:33], v[136:139], v[184:187], v[30:33]
	v_mfma_f32_16x16x32_bf16 v[26:29], v[144:147], v[184:187], v[26:29]
	v_mfma_f32_16x16x32_bf16 v[14:17], v[136:139], v[192:195], v[14:17]
	v_mfma_f32_16x16x32_bf16 v[10:13], v[144:147], v[192:195], v[10:13]
	v_mfma_f32_16x16x32_bf16 v[62:65], v[140:143], v[172:175], v[62:65]
	v_mfma_f32_16x16x32_bf16 v[58:61], v[148:151], v[172:175], v[58:61]
	v_mfma_f32_16x16x32_bf16 v[46:49], v[140:143], v[180:183], v[46:49]
	v_mfma_f32_16x16x32_bf16 v[42:45], v[148:151], v[180:183], v[42:45]
	v_mfma_f32_16x16x32_bf16 v[30:33], v[140:143], v[188:191], v[30:33]
	v_mfma_f32_16x16x32_bf16 v[26:29], v[148:151], v[188:191], v[26:29]
	v_mfma_f32_16x16x32_bf16 v[14:17], v[140:143], v[196:199], v[14:17]
	v_mfma_f32_16x16x32_bf16 v[10:13], v[148:151], v[196:199], v[10:13]
	v_mfma_f32_16x16x32_bf16 v[54:57], v[152:155], v[168:171], v[54:57]
	v_mfma_f32_16x16x32_bf16 v[50:53], v[160:163], v[168:171], v[50:53]
	v_mfma_f32_16x16x32_bf16 v[38:41], v[152:155], v[176:179], v[38:41]
	v_mfma_f32_16x16x32_bf16 v[34:37], v[160:163], v[176:179], v[34:37]
	v_mfma_f32_16x16x32_bf16 v[22:25], v[152:155], v[184:187], v[22:25]
	v_mfma_f32_16x16x32_bf16 v[18:21], v[160:163], v[184:187], v[18:21]
	v_mfma_f32_16x16x32_bf16 v[6:9], v[152:155], v[192:195], v[6:9]
	v_mfma_f32_16x16x32_bf16 v[2:5], v[160:163], v[192:195], v[2:5]
	v_mfma_f32_16x16x32_bf16 v[54:57], v[156:159], v[172:175], v[54:57]
	v_mfma_f32_16x16x32_bf16 v[50:53], v[164:167], v[172:175], v[50:53]
	v_mfma_f32_16x16x32_bf16 v[38:41], v[156:159], v[180:183], v[38:41]
	v_mfma_f32_16x16x32_bf16 v[34:37], v[164:167], v[180:183], v[34:37]
	v_mfma_f32_16x16x32_bf16 v[22:25], v[156:159], v[188:191], v[22:25]
	v_mfma_f32_16x16x32_bf16 v[18:21], v[164:167], v[188:191], v[18:21]
	v_mfma_f32_16x16x32_bf16 v[6:9], v[156:159], v[196:199], v[6:9]
	v_mfma_f32_16x16x32_bf16 v[2:5], v[164:167], v[196:199], v[2:5]
	s_setprio 0
	s_barrier
	v_add_u32_e32 v0, 0x18000, v134
	ds_read_b128 v[136:139], v0
	ds_read_b128 v[140:143], v0 offset:1024
	ds_read_b128 v[144:147], v0 offset:2048
	ds_read_b128 v[148:151], v0 offset:3072
	v_add_u32_e32 v0, 0x1c000, v134
	ds_read_b128 v[152:155], v0
	ds_read_b128 v[156:159], v0 offset:1024
	ds_read_b128 v[160:163], v0 offset:2048
	ds_read_b128 v[164:167], v0 offset:3072
	ds_read_b128 v[168:171], v135 offset:32768
	ds_read_b128 v[172:175], v135 offset:33792
	ds_read_b128 v[176:179], v135 offset:34816
	ds_read_b128 v[180:183], v135 offset:35840
	ds_read_b128 v[184:187], v135 offset:36864
	ds_read_b128 v[188:191], v135 offset:37888
	ds_read_b128 v[192:195], v135 offset:38912
	ds_read_b128 v[196:199], v135 offset:39936
	s_add_u32 s56, s56, s4
	s_addc_u32 s57, s57, s5
	s_mov_b32 s76, m0
	s_mov_b32 m0, s61
	s_nop 0
	global_load_lds_dwordx4 v130, s[56:57]
	s_mov_b32 m0, s62
	s_nop 0
	global_load_lds_dwordx4 v132, s[56:57]
	s_mov_b32 m0, s76
	s_waitcnt vmcnt(8)
	s_waitcnt lgkmcnt(0)
	s_barrier
	s_setprio 1
	v_mfma_f32_16x16x32_bf16 v[126:129], v[136:139], v[168:171], v[126:129]
	v_mfma_f32_16x16x32_bf16 v[122:125], v[144:147], v[168:171], v[122:125]
	v_mfma_f32_16x16x32_bf16 v[110:113], v[136:139], v[176:179], v[110:113]
	v_mfma_f32_16x16x32_bf16 v[106:109], v[144:147], v[176:179], v[106:109]
	v_mfma_f32_16x16x32_bf16 v[94:97], v[136:139], v[184:187], v[94:97]
	v_mfma_f32_16x16x32_bf16 v[90:93], v[144:147], v[184:187], v[90:93]
	v_mfma_f32_16x16x32_bf16 v[78:81], v[136:139], v[192:195], v[78:81]
	v_mfma_f32_16x16x32_bf16 v[74:77], v[144:147], v[192:195], v[74:77]
	v_mfma_f32_16x16x32_bf16 v[126:129], v[140:143], v[172:175], v[126:129]
	v_mfma_f32_16x16x32_bf16 v[122:125], v[148:151], v[172:175], v[122:125]
	v_mfma_f32_16x16x32_bf16 v[110:113], v[140:143], v[180:183], v[110:113]
	v_mfma_f32_16x16x32_bf16 v[106:109], v[148:151], v[180:183], v[106:109]
	v_mfma_f32_16x16x32_bf16 v[94:97], v[140:143], v[188:191], v[94:97]
	v_mfma_f32_16x16x32_bf16 v[90:93], v[148:151], v[188:191], v[90:93]
	v_mfma_f32_16x16x32_bf16 v[78:81], v[140:143], v[196:199], v[78:81]
	v_mfma_f32_16x16x32_bf16 v[74:77], v[148:151], v[196:199], v[74:77]
	v_mfma_f32_16x16x32_bf16 v[118:121], v[152:155], v[168:171], v[118:121]
	v_mfma_f32_16x16x32_bf16 v[114:117], v[160:163], v[168:171], v[114:117]
	v_mfma_f32_16x16x32_bf16 v[102:105], v[152:155], v[176:179], v[102:105]
	v_mfma_f32_16x16x32_bf16 v[98:101], v[160:163], v[176:179], v[98:101]
	v_mfma_f32_16x16x32_bf16 v[86:89], v[152:155], v[184:187], v[86:89]
	v_mfma_f32_16x16x32_bf16 v[82:85], v[160:163], v[184:187], v[82:85]
	v_mfma_f32_16x16x32_bf16 v[70:73], v[152:155], v[192:195], v[70:73]
	v_mfma_f32_16x16x32_bf16 v[66:69], v[160:163], v[192:195], v[66:69]
	v_mfma_f32_16x16x32_bf16 v[118:121], v[156:159], v[172:175], v[118:121]
	v_mfma_f32_16x16x32_bf16 v[114:117], v[164:167], v[172:175], v[114:117]
	v_mfma_f32_16x16x32_bf16 v[102:105], v[156:159], v[180:183], v[102:105]
	v_mfma_f32_16x16x32_bf16 v[98:101], v[164:167], v[180:183], v[98:101]
	v_mfma_f32_16x16x32_bf16 v[86:89], v[156:159], v[188:191], v[86:89]
	v_mfma_f32_16x16x32_bf16 v[82:85], v[164:167], v[188:191], v[82:85]
	v_mfma_f32_16x16x32_bf16 v[70:73], v[156:159], v[196:199], v[70:73]
	v_mfma_f32_16x16x32_bf16 v[66:69], v[164:167], v[196:199], v[66:69]
	s_setprio 0
	s_barrier
	ds_read_b128 v[168:171], v135 offset:49152
	ds_read_b128 v[172:175], v135 offset:50176
	ds_read_b128 v[176:179], v135 offset:51200
	ds_read_b128 v[180:183], v135 offset:52224
	ds_read_b128 v[184:187], v135 offset:53248
	ds_read_b128 v[188:191], v135 offset:54272
	ds_read_b128 v[192:195], v135 offset:55296
	ds_read_b128 v[196:199], v135 offset:56320
	s_add_u32 s54, s54, 0x80
	s_addc_u32 s55, s55, 0
	s_mov_b32 s56, m0
	s_mov_b32 m0, s65
	s_nop 0
	global_load_lds_dwordx4 v131, s[54:55]
	s_mov_b32 m0, s66
	s_nop 0
	global_load_lds_dwordx4 v133, s[54:55]
	s_mov_b32 m0, s56
	s_add_u32 s54, s58, 0x80
	s_addc_u32 s55, s59, 0
	s_mov_b32 s56, m0
	s_mov_b32 m0, s69
	s_nop 0
	global_load_lds_dwordx4 v131, s[54:55]
	s_mov_b32 m0, s70
	s_nop 0
	global_load_lds_dwordx4 v133, s[54:55]
	s_mov_b32 m0, s56
	s_mov_b32 s54, m0
	s_mov_b32 m0, s67
	s_nop 0
	global_load_lds_dwordx4 v130, s[52:53]
	s_mov_b32 m0, s68
	s_nop 0
	global_load_lds_dwordx4 v132, s[52:53]
	s_mov_b32 m0, s54
	s_waitcnt vmcnt(8)
	s_waitcnt lgkmcnt(0)
	s_barrier
	s_setprio 1
	v_mfma_f32_16x16x32_bf16 v[62:65], v[136:139], v[168:171], v[62:65]
	v_mfma_f32_16x16x32_bf16 v[58:61], v[144:147], v[168:171], v[58:61]
	v_mfma_f32_16x16x32_bf16 v[46:49], v[136:139], v[176:179], v[46:49]
	v_mfma_f32_16x16x32_bf16 v[42:45], v[144:147], v[176:179], v[42:45]
	v_mfma_f32_16x16x32_bf16 v[30:33], v[136:139], v[184:187], v[30:33]
	v_mfma_f32_16x16x32_bf16 v[26:29], v[144:147], v[184:187], v[26:29]
	v_mfma_f32_16x16x32_bf16 v[14:17], v[136:139], v[192:195], v[14:17]
	v_mfma_f32_16x16x32_bf16 v[10:13], v[144:147], v[192:195], v[10:13]
	v_mfma_f32_16x16x32_bf16 v[62:65], v[140:143], v[172:175], v[62:65]
	v_mfma_f32_16x16x32_bf16 v[58:61], v[148:151], v[172:175], v[58:61]
	v_mfma_f32_16x16x32_bf16 v[46:49], v[140:143], v[180:183], v[46:49]
	v_mfma_f32_16x16x32_bf16 v[42:45], v[148:151], v[180:183], v[42:45]
	v_mfma_f32_16x16x32_bf16 v[30:33], v[140:143], v[188:191], v[30:33]
	v_mfma_f32_16x16x32_bf16 v[26:29], v[148:151], v[188:191], v[26:29]
	v_mfma_f32_16x16x32_bf16 v[14:17], v[140:143], v[196:199], v[14:17]
	v_mfma_f32_16x16x32_bf16 v[10:13], v[148:151], v[196:199], v[10:13]
	v_mfma_f32_16x16x32_bf16 v[54:57], v[152:155], v[168:171], v[54:57]
	v_mfma_f32_16x16x32_bf16 v[50:53], v[160:163], v[168:171], v[50:53]
	v_mfma_f32_16x16x32_bf16 v[38:41], v[152:155], v[176:179], v[38:41]
	v_mfma_f32_16x16x32_bf16 v[34:37], v[160:163], v[176:179], v[34:37]
	v_mfma_f32_16x16x32_bf16 v[22:25], v[152:155], v[184:187], v[22:25]
	v_mfma_f32_16x16x32_bf16 v[18:21], v[160:163], v[184:187], v[18:21]
	v_mfma_f32_16x16x32_bf16 v[6:9], v[152:155], v[192:195], v[6:9]
	v_mfma_f32_16x16x32_bf16 v[2:5], v[160:163], v[192:195], v[2:5]
	v_mfma_f32_16x16x32_bf16 v[54:57], v[156:159], v[172:175], v[54:57]
	v_mfma_f32_16x16x32_bf16 v[50:53], v[164:167], v[172:175], v[50:53]
	v_mfma_f32_16x16x32_bf16 v[38:41], v[156:159], v[180:183], v[38:41]
	v_mfma_f32_16x16x32_bf16 v[34:37], v[164:167], v[180:183], v[34:37]
	v_mfma_f32_16x16x32_bf16 v[22:25], v[156:159], v[188:191], v[22:25]
	v_mfma_f32_16x16x32_bf16 v[18:21], v[164:167], v[188:191], v[18:21]
	v_mfma_f32_16x16x32_bf16 v[6:9], v[156:159], v[196:199], v[6:9]
	v_mfma_f32_16x16x32_bf16 v[2:5], v[164:167], v[196:199], v[2:5]
	s_setprio 0
	s_barrier
	s_add_i32 s51, s51, 2
	s_add_u32 s24, s24, 0x100
	s_addc_u32 s25, s25, 0
	s_add_u32 s26, s26, 0x100
	s_addc_u32 s27, s27, 0
	s_cmp_gt_u32 s51, 13
	s_cbranch_scc0 .LBB0_95
	s_and_b64 vcc, exec, s[46:47]
	s_cbranch_vccz .LBB0_98
	s_barrier

.LBB0_122:
	s_add_u32 s56, s27, s54
	v_add_u32_e32 v0, 0x10000, v168
	s_addc_u32 s57, s53, s55
	ds_read_b128 v[130:133], v0
	ds_read_b128 v[134:137], v0 offset:1024
	ds_read_b128 v[138:141], v0 offset:2048
	ds_read_b128 v[142:145], v0 offset:3072
	v_add_u32_e32 v0, 0x14000, v168
	s_add_u32 s58, s48, s54
	ds_read_b128 v[146:149], v0
	ds_read_b128 v[150:153], v0 offset:1024
	ds_read_b128 v[154:157], v0 offset:2048
	ds_read_b128 v[158:161], v0 offset:3072
	s_addc_u32 s59, s49, s55
	s_add_u32 s58, s58, 0x100
	s_addc_u32 s59, s59, 0
	s_cmp_eq_u32 s91, 12
	s_cselect_b32 s60, s50, s56
	s_cselect_b32 s61, s51, s57
	s_cselect_b32 s58, s42, s58
	s_cselect_b32 s59, s43, s59
	s_add_u32 s56, s60, 0x80
	s_addc_u32 s57, s61, 0
	ds_read_b128 v[170:173], v169
	ds_read_b128 v[174:177], v169 offset:1024
	ds_read_b128 v[178:181], v169 offset:2048
	ds_read_b128 v[182:185], v169 offset:3072
	ds_read_b128 v[186:189], v169 offset:4096
	ds_read_b128 v[190:193], v169 offset:5120
	ds_read_b128 v[194:197], v169 offset:6144
	ds_read_b128 v[198:201], v169 offset:7168
	s_add_u32 s62, s76, s54
	s_addc_u32 s63, s90, s55
	s_mov_b32 s92, m0
	s_mov_b32 m0, s85
	s_nop 0
	global_load_lds_dwordx4 v164, s[62:63]
	s_mov_b32 m0, s86
	s_nop 0
	global_load_lds_dwordx4 v166, s[62:63]
	s_mov_b32 m0, s92
	s_waitcnt vmcnt(8)
	s_waitcnt lgkmcnt(0)
	s_barrier
	s_setprio 1
	v_mfma_f32_16x16x32_bf16 v[126:129], v[130:133], v[170:173], v[126:129]
	v_mfma_f32_16x16x32_bf16 v[122:125], v[138:141], v[170:173], v[122:125]
	v_mfma_f32_16x16x32_bf16 v[118:121], v[130:133], v[178:181], v[118:121]
	v_mfma_f32_16x16x32_bf16 v[114:117], v[138:141], v[178:181], v[114:117]
	v_mfma_f32_16x16x32_bf16 v[110:113], v[130:133], v[186:189], v[110:113]
	v_mfma_f32_16x16x32_bf16 v[106:109], v[138:141], v[186:189], v[106:109]
	v_mfma_f32_16x16x32_bf16 v[102:105], v[130:133], v[194:197], v[102:105]
	v_mfma_f32_16x16x32_bf16 v[98:101], v[138:141], v[194:197], v[98:101]
	v_mfma_f32_16x16x32_bf16 v[126:129], v[134:137], v[174:177], v[126:129]
	v_mfma_f32_16x16x32_bf16 v[122:125], v[142:145], v[174:177], v[122:125]
	v_mfma_f32_16x16x32_bf16 v[118:121], v[134:137], v[182:185], v[118:121]
	v_mfma_f32_16x16x32_bf16 v[114:117], v[142:145], v[182:185], v[114:117]
	v_mfma_f32_16x16x32_bf16 v[110:113], v[134:137], v[190:193], v[110:113]
	v_mfma_f32_16x16x32_bf16 v[106:109], v[142:145], v[190:193], v[106:109]
	v_mfma_f32_16x16x32_bf16 v[102:105], v[134:137], v[198:201], v[102:105]
	v_mfma_f32_16x16x32_bf16 v[98:101], v[142:145], v[198:201], v[98:101]
	v_mfma_f32_16x16x32_bf16 v[94:97], v[146:149], v[170:173], v[94:97]
	v_mfma_f32_16x16x32_bf16 v[90:93], v[154:157], v[170:173], v[90:93]
	v_mfma_f32_16x16x32_bf16 v[86:89], v[146:149], v[178:181], v[86:89]
	v_mfma_f32_16x16x32_bf16 v[82:85], v[154:157], v[178:181], v[82:85]
	v_mfma_f32_16x16x32_bf16 v[78:81], v[146:149], v[186:189], v[78:81]
	v_mfma_f32_16x16x32_bf16 v[74:77], v[154:157], v[186:189], v[74:77]
	v_mfma_f32_16x16x32_bf16 v[70:73], v[146:149], v[194:197], v[70:73]
	v_mfma_f32_16x16x32_bf16 v[66:69], v[154:157], v[194:197], v[66:69]
	v_mfma_f32_16x16x32_bf16 v[94:97], v[150:153], v[174:177], v[94:97]
	v_mfma_f32_16x16x32_bf16 v[90:93], v[158:161], v[174:177], v[90:93]
	v_mfma_f32_16x16x32_bf16 v[86:89], v[150:153], v[182:185], v[86:89]
	v_mfma_f32_16x16x32_bf16 v[82:85], v[158:161], v[182:185], v[82:85]
	v_mfma_f32_16x16x32_bf16 v[78:81], v[150:153], v[190:193], v[78:81]
	v_mfma_f32_16x16x32_bf16 v[74:77], v[158:161], v[190:193], v[74:77]
	v_mfma_f32_16x16x32_bf16 v[70:73], v[150:153], v[198:201], v[70:73]
	v_mfma_f32_16x16x32_bf16 v[66:69], v[158:161], v[198:201], v[66:69]
	s_setprio 0
	s_barrier
	ds_read_b128 v[170:173], v169 offset:16384
	ds_read_b128 v[174:177], v169 offset:17408
	ds_read_b128 v[178:181], v169 offset:18432
	ds_read_b128 v[182:185], v169 offset:19456
	ds_read_b128 v[186:189], v169 offset:20480
	ds_read_b128 v[190:193], v169 offset:21504
	ds_read_b128 v[194:197], v169 offset:22528
	ds_read_b128 v[198:201], v169 offset:23552
	s_mov_b32 s62, m0
	s_mov_b32 m0, s30
	s_nop 0
	global_load_lds_dwordx4 v165, s[58:59]
	s_mov_b32 m0, s31
	s_nop 0
	global_load_lds_dwordx4 v167, s[58:59]
	s_mov_b32 m0, s62
	s_add_u32 s62, s58, s20
	s_addc_u32 s63, s59, s21
	s_mov_b32 s92, m0
	s_mov_b32 m0, s64
	s_nop 0
	global_load_lds_dwordx4 v165, s[62:63]
	s_mov_b32 m0, s65
	s_nop 0
	global_load_lds_dwordx4 v167, s[62:63]
	s_mov_b32 m0, s92
	s_nop 0
	s_mov_b32 s92, m0
	s_mov_b32 m0, s29
	s_nop 0
	global_load_lds_dwordx4 v164, s[60:61]
	s_mov_b32 m0, s66
	s_nop 0
	global_load_lds_dwordx4 v166, s[60:61]
	s_mov_b32 m0, s92
	s_waitcnt vmcnt(8)
	s_waitcnt lgkmcnt(0)
	s_barrier
	s_setprio 1
	v_mfma_f32_16x16x32_bf16 v[62:65], v[130:133], v[170:173], v[62:65]
	v_mfma_f32_16x16x32_bf16 v[58:61], v[138:141], v[170:173], v[58:61]
	v_mfma_f32_16x16x32_bf16 v[54:57], v[130:133], v[178:181], v[54:57]
	v_mfma_f32_16x16x32_bf16 v[50:53], v[138:141], v[178:181], v[50:53]
	v_mfma_f32_16x16x32_bf16 v[46:49], v[130:133], v[186:189], v[46:49]
	v_mfma_f32_16x16x32_bf16 v[42:45], v[138:141], v[186:189], v[42:45]
	v_mfma_f32_16x16x32_bf16 v[38:41], v[130:133], v[194:197], v[38:41]
	v_mfma_f32_16x16x32_bf16 v[34:37], v[138:141], v[194:197], v[34:37]
	v_mfma_f32_16x16x32_bf16 v[62:65], v[134:137], v[174:177], v[62:65]
	v_mfma_f32_16x16x32_bf16 v[58:61], v[142:145], v[174:177], v[58:61]
	v_mfma_f32_16x16x32_bf16 v[54:57], v[134:137], v[182:185], v[54:57]
	v_mfma_f32_16x16x32_bf16 v[50:53], v[142:145], v[182:185], v[50:53]
	v_mfma_f32_16x16x32_bf16 v[46:49], v[134:137], v[190:193], v[46:49]
	v_mfma_f32_16x16x32_bf16 v[42:45], v[142:145], v[190:193], v[42:45]
	v_mfma_f32_16x16x32_bf16 v[38:41], v[134:137], v[198:201], v[38:41]
	v_mfma_f32_16x16x32_bf16 v[34:37], v[142:145], v[198:201], v[34:37]
	v_mfma_f32_16x16x32_bf16 v[30:33], v[146:149], v[170:173], v[30:33]
	v_mfma_f32_16x16x32_bf16 v[26:29], v[154:157], v[170:173], v[26:29]
	v_mfma_f32_16x16x32_bf16 v[22:25], v[146:149], v[178:181], v[22:25]
	v_mfma_f32_16x16x32_bf16 v[18:21], v[154:157], v[178:181], v[18:21]
	v_mfma_f32_16x16x32_bf16 v[14:17], v[146:149], v[186:189], v[14:17]
	v_mfma_f32_16x16x32_bf16 v[10:13], v[154:157], v[186:189], v[10:13]
	v_mfma_f32_16x16x32_bf16 v[6:9], v[146:149], v[194:197], v[6:9]
	v_mfma_f32_16x16x32_bf16 v[2:5], v[154:157], v[194:197], v[2:5]
	v_mfma_f32_16x16x32_bf16 v[30:33], v[150:153], v[174:177], v[30:33]
	v_mfma_f32_16x16x32_bf16 v[26:29], v[158:161], v[174:177], v[26:29]
	v_mfma_f32_16x16x32_bf16 v[22:25], v[150:153], v[182:185], v[22:25]
	v_mfma_f32_16x16x32_bf16 v[18:21], v[158:161], v[182:185], v[18:21]
	v_mfma_f32_16x16x32_bf16 v[14:17], v[150:153], v[190:193], v[14:17]
	v_mfma_f32_16x16x32_bf16 v[10:13], v[158:161], v[190:193], v[10:13]
	v_mfma_f32_16x16x32_bf16 v[6:9], v[150:153], v[198:201], v[6:9]
	v_mfma_f32_16x16x32_bf16 v[2:5], v[158:161], v[198:201], v[2:5]
	s_setprio 0
	s_barrier
	v_add_u32_e32 v0, 0x18000, v168
	ds_read_b128 v[130:133], v0
	ds_read_b128 v[134:137], v0 offset:1024
	ds_read_b128 v[138:141], v0 offset:2048
	ds_read_b128 v[142:145], v0 offset:3072
	v_add_u32_e32 v0, 0x1c000, v168
	ds_read_b128 v[146:149], v0
	ds_read_b128 v[150:153], v0 offset:1024
	ds_read_b128 v[154:157], v0 offset:2048
	ds_read_b128 v[158:161], v0 offset:3072
	ds_read_b128 v[170:173], v169 offset:32768
	ds_read_b128 v[174:177], v169 offset:33792
	ds_read_b128 v[178:181], v169 offset:34816
	ds_read_b128 v[182:185], v169 offset:35840
	ds_read_b128 v[186:189], v169 offset:36864
	ds_read_b128 v[190:193], v169 offset:37888
	ds_read_b128 v[194:197], v169 offset:38912
	ds_read_b128 v[198:201], v169 offset:39936
	s_add_u32 s60, s60, s4
	s_addc_u32 s61, s61, s5
	s_mov_b32 s92, m0
	s_mov_b32 m0, s68
	s_nop 0
	global_load_lds_dwordx4 v164, s[60:61]
	s_mov_b32 m0, s69
	s_nop 0
	global_load_lds_dwordx4 v166, s[60:61]
	s_mov_b32 m0, s92
	s_waitcnt vmcnt(8)
	s_waitcnt lgkmcnt(0)
	s_barrier
	s_setprio 1
	v_mfma_f32_16x16x32_bf16 v[126:129], v[130:133], v[170:173], v[126:129]
	v_mfma_f32_16x16x32_bf16 v[122:125], v[138:141], v[170:173], v[122:125]
	v_mfma_f32_16x16x32_bf16 v[118:121], v[130:133], v[178:181], v[118:121]
	v_mfma_f32_16x16x32_bf16 v[114:117], v[138:141], v[178:181], v[114:117]
	v_mfma_f32_16x16x32_bf16 v[110:113], v[130:133], v[186:189], v[110:113]
	v_mfma_f32_16x16x32_bf16 v[106:109], v[138:141], v[186:189], v[106:109]
	v_mfma_f32_16x16x32_bf16 v[102:105], v[130:133], v[194:197], v[102:105]
	v_mfma_f32_16x16x32_bf16 v[98:101], v[138:141], v[194:197], v[98:101]
	v_mfma_f32_16x16x32_bf16 v[126:129], v[134:137], v[174:177], v[126:129]
	v_mfma_f32_16x16x32_bf16 v[122:125], v[142:145], v[174:177], v[122:125]
	v_mfma_f32_16x16x32_bf16 v[118:121], v[134:137], v[182:185], v[118:121]
	v_mfma_f32_16x16x32_bf16 v[114:117], v[142:145], v[182:185], v[114:117]
	v_mfma_f32_16x16x32_bf16 v[110:113], v[134:137], v[190:193], v[110:113]
	v_mfma_f32_16x16x32_bf16 v[106:109], v[142:145], v[190:193], v[106:109]
	v_mfma_f32_16x16x32_bf16 v[102:105], v[134:137], v[198:201], v[102:105]
	v_mfma_f32_16x16x32_bf16 v[98:101], v[142:145], v[198:201], v[98:101]
	v_mfma_f32_16x16x32_bf16 v[94:97], v[146:149], v[170:173], v[94:97]
	v_mfma_f32_16x16x32_bf16 v[90:93], v[154:157], v[170:173], v[90:93]
	v_mfma_f32_16x16x32_bf16 v[86:89], v[146:149], v[178:181], v[86:89]
	v_mfma_f32_16x16x32_bf16 v[82:85], v[154:157], v[178:181], v[82:85]
	v_mfma_f32_16x16x32_bf16 v[78:81], v[146:149], v[186:189], v[78:81]
	v_mfma_f32_16x16x32_bf16 v[74:77], v[154:157], v[186:189], v[74:77]
	v_mfma_f32_16x16x32_bf16 v[70:73], v[146:149], v[194:197], v[70:73]
	v_mfma_f32_16x16x32_bf16 v[66:69], v[154:157], v[194:197], v[66:69]
	v_mfma_f32_16x16x32_bf16 v[94:97], v[150:153], v[174:177], v[94:97]
	v_mfma_f32_16x16x32_bf16 v[90:93], v[158:161], v[174:177], v[90:93]
	v_mfma_f32_16x16x32_bf16 v[86:89], v[150:153], v[182:185], v[86:89]
	v_mfma_f32_16x16x32_bf16 v[82:85], v[158:161], v[182:185], v[82:85]
	v_mfma_f32_16x16x32_bf16 v[78:81], v[150:153], v[190:193], v[78:81]
	v_mfma_f32_16x16x32_bf16 v[74:77], v[158:161], v[190:193], v[74:77]
	v_mfma_f32_16x16x32_bf16 v[70:73], v[150:153], v[198:201], v[70:73]
	v_mfma_f32_16x16x32_bf16 v[66:69], v[158:161], v[198:201], v[66:69]
	s_setprio 0
	s_barrier
	ds_read_b128 v[170:173], v169 offset:49152
	ds_read_b128 v[174:177], v169 offset:50176
	ds_read_b128 v[178:181], v169 offset:51200
	ds_read_b128 v[182:185], v169 offset:52224
	ds_read_b128 v[186:189], v169 offset:53248
	ds_read_b128 v[190:193], v169 offset:54272
	ds_read_b128 v[194:197], v169 offset:55296
	ds_read_b128 v[198:201], v169 offset:56320
	s_add_u32 s58, s58, 0x80
	s_addc_u32 s59, s59, 0
	s_mov_b32 s60, m0
	s_mov_b32 m0, s75
	s_nop 0
	global_load_lds_dwordx4 v165, s[58:59]
	s_mov_b32 m0, s80
	s_nop 0
	global_load_lds_dwordx4 v167, s[58:59]
	s_mov_b32 m0, s60
	s_add_u32 s58, s62, 0x80
	s_addc_u32 s59, s63, 0
	s_mov_b32 s60, m0
	s_mov_b32 m0, s83
	s_nop 0
	global_load_lds_dwordx4 v165, s[58:59]
	s_mov_b32 m0, s84
	s_nop 0
	global_load_lds_dwordx4 v167, s[58:59]
	s_mov_b32 m0, s60
	s_mov_b32 s58, m0
	s_mov_b32 m0, s81
	s_nop 0
	global_load_lds_dwordx4 v164, s[56:57]
	s_mov_b32 m0, s82
	s_nop 0
	global_load_lds_dwordx4 v166, s[56:57]
	s_mov_b32 m0, s58
	s_waitcnt vmcnt(8)
	s_waitcnt lgkmcnt(0)
	s_barrier
	s_setprio 1
	v_mfma_f32_16x16x32_bf16 v[62:65], v[130:133], v[170:173], v[62:65]
	v_mfma_f32_16x16x32_bf16 v[58:61], v[138:141], v[170:173], v[58:61]
	v_mfma_f32_16x16x32_bf16 v[54:57], v[130:133], v[178:181], v[54:57]
	v_mfma_f32_16x16x32_bf16 v[50:53], v[138:141], v[178:181], v[50:53]
	v_mfma_f32_16x16x32_bf16 v[46:49], v[130:133], v[186:189], v[46:49]
	v_mfma_f32_16x16x32_bf16 v[42:45], v[138:141], v[186:189], v[42:45]
	v_mfma_f32_16x16x32_bf16 v[38:41], v[130:133], v[194:197], v[38:41]
	v_mfma_f32_16x16x32_bf16 v[34:37], v[138:141], v[194:197], v[34:37]
	v_mfma_f32_16x16x32_bf16 v[62:65], v[134:137], v[174:177], v[62:65]
	v_mfma_f32_16x16x32_bf16 v[58:61], v[142:145], v[174:177], v[58:61]
	v_mfma_f32_16x16x32_bf16 v[54:57], v[134:137], v[182:185], v[54:57]
	v_mfma_f32_16x16x32_bf16 v[50:53], v[142:145], v[182:185], v[50:53]
	v_mfma_f32_16x16x32_bf16 v[46:49], v[134:137], v[190:193], v[46:49]
	v_mfma_f32_16x16x32_bf16 v[42:45], v[142:145], v[190:193], v[42:45]
	v_mfma_f32_16x16x32_bf16 v[38:41], v[134:137], v[198:201], v[38:41]
	v_mfma_f32_16x16x32_bf16 v[34:37], v[142:145], v[198:201], v[34:37]
	v_mfma_f32_16x16x32_bf16 v[30:33], v[146:149], v[170:173], v[30:33]
	v_mfma_f32_16x16x32_bf16 v[26:29], v[154:157], v[170:173], v[26:29]
	v_mfma_f32_16x16x32_bf16 v[22:25], v[146:149], v[178:181], v[22:25]
	v_mfma_f32_16x16x32_bf16 v[18:21], v[154:157], v[178:181], v[18:21]
	v_mfma_f32_16x16x32_bf16 v[14:17], v[146:149], v[186:189], v[14:17]
	v_mfma_f32_16x16x32_bf16 v[10:13], v[154:157], v[186:189], v[10:13]
	v_mfma_f32_16x16x32_bf16 v[6:9], v[146:149], v[194:197], v[6:9]
	v_mfma_f32_16x16x32_bf16 v[2:5], v[154:157], v[194:197], v[2:5]
	v_mfma_f32_16x16x32_bf16 v[30:33], v[150:153], v[174:177], v[30:33]
	v_mfma_f32_16x16x32_bf16 v[26:29], v[158:161], v[174:177], v[26:29]
	v_mfma_f32_16x16x32_bf16 v[22:25], v[150:153], v[182:185], v[22:25]
	v_mfma_f32_16x16x32_bf16 v[18:21], v[158:161], v[182:185], v[18:21]
	v_mfma_f32_16x16x32_bf16 v[14:17], v[150:153], v[190:193], v[14:17]
	v_mfma_f32_16x16x32_bf16 v[10:13], v[158:161], v[190:193], v[10:13]
	v_mfma_f32_16x16x32_bf16 v[6:9], v[150:153], v[198:201], v[6:9]
	v_mfma_f32_16x16x32_bf16 v[2:5], v[158:161], v[198:201], v[2:5]
	s_setprio 0
	s_barrier
	s_add_i32 s91, s91, 2
	s_add_u32 s54, s54, 0x100
	s_addc_u32 s55, s55, 0
	s_cmp_gt_u32 s91, 13
	s_cbranch_scc0 .LBB0_122
	s_and_b64 vcc, exec, s[46:47]
	s_cbranch_vccz .LBB0_125
	s_barrier

.LBB0_372:
	s_add_u32 s26, s42, s25
	s_addc_u32 s27, s43, 0
	s_add_u32 s30, s26, 0x100
	s_addc_u32 s31, s27, 0
	s_and_b64 s[26:27], s[56:57], exec
	s_cselect_b32 s65, s53, s31
	s_cselect_b32 s64, s52, s30
	s_add_u32 s26, s44, s25
	s_addc_u32 s27, s45, 0
	s_add_u32 s30, s26, 0x100
	s_addc_u32 s31, s27, 0
	s_add_u32 s58, s64, 0x80
	s_addc_u32 s59, s65, 0
	s_and_b64 s[26:27], s[56:57], exec
	s_cselect_b32 s67, s55, s31
	s_cselect_b32 s66, s54, s30
	s_add_u32 s25, s10, s25
	s_addc_u32 s26, s24, 0
	s_add_u32 s70, s25, 0x80
	s_addc_u32 s71, s26, 0
	v_add_u32_e32 v0, 0x10000, v154
	s_add_u32 s68, s66, s20
	ds_read_b128 v[38:41], v0
	ds_read_b128 v[42:45], v0 offset:1024
	ds_read_b128 v[50:53], v0 offset:2048
	ds_read_b128 v[54:57], v0 offset:3072
	v_add_u32_e32 v0, 0x14000, v154
	s_addc_u32 s69, s67, s21
	ds_read_b128 v[146:149], v0
	ds_read_b128 v[156:159], v0 offset:1024
	ds_read_b128 v[160:163], v0 offset:2048
	ds_read_b128 v[164:167], v0 offset:3072
	s_add_u32 s62, s64, s4
	s_addc_u32 s63, s65, s5
	s_add_u32 s60, s66, 0x80
	s_addc_u32 s61, s67, 0
	s_add_u32 s56, s68, 0x80
	s_addc_u32 s57, s69, 0
	ds_read_b128 v[168:171], v155
	ds_read_b128 v[172:175], v155 offset:1024
	ds_read_b128 v[176:179], v155 offset:2048
	ds_read_b128 v[202:205], v155 offset:3072
	ds_read_b128 v[206:209], v155 offset:4096
	ds_read_b128 v[216:219], v155 offset:5120
	ds_read_b128 v[220:223], v155 offset:6144
	ds_read_b128 v[224:227], v155 offset:7168
	s_mov_b32 s25, m0
	s_mov_b32 m0, s46
	s_nop 0
	global_load_lds_dwordx4 v150, s[70:71]
	s_mov_b32 m0, s47
	s_nop 0
	global_load_lds_dwordx4 v152, s[70:71]
	s_mov_b32 m0, s25
	s_waitcnt vmcnt(8)
	s_waitcnt lgkmcnt(0)
	s_barrier
	s_setprio 1
	v_mfma_f32_16x16x32_bf16 v[142:145], v[38:41], v[168:171], v[142:145]
	v_mfma_f32_16x16x32_bf16 v[138:141], v[50:53], v[168:171], v[138:141]
	v_mfma_f32_16x16x32_bf16 v[126:129], v[38:41], v[176:179], v[126:129]
	v_mfma_f32_16x16x32_bf16 v[122:125], v[50:53], v[176:179], v[122:125]
	v_mfma_f32_16x16x32_bf16 v[110:113], v[38:41], v[206:209], v[110:113]
	v_mfma_f32_16x16x32_bf16 v[106:109], v[50:53], v[206:209], v[106:109]
	v_mfma_f32_16x16x32_bf16 v[94:97], v[38:41], v[220:223], v[94:97]
	v_mfma_f32_16x16x32_bf16 v[90:93], v[50:53], v[220:223], v[90:93]
	v_mfma_f32_16x16x32_bf16 v[142:145], v[42:45], v[172:175], v[142:145]
	v_mfma_f32_16x16x32_bf16 v[138:141], v[54:57], v[172:175], v[138:141]
	v_mfma_f32_16x16x32_bf16 v[126:129], v[42:45], v[202:205], v[126:129]
	v_mfma_f32_16x16x32_bf16 v[122:125], v[54:57], v[202:205], v[122:125]
	v_mfma_f32_16x16x32_bf16 v[110:113], v[42:45], v[216:219], v[110:113]
	v_mfma_f32_16x16x32_bf16 v[106:109], v[54:57], v[216:219], v[106:109]
	v_mfma_f32_16x16x32_bf16 v[94:97], v[42:45], v[224:227], v[94:97]
	v_mfma_f32_16x16x32_bf16 v[90:93], v[54:57], v[224:227], v[90:93]
	v_mfma_f32_16x16x32_bf16 v[134:137], v[146:149], v[168:171], v[134:137]
	v_mfma_f32_16x16x32_bf16 v[130:133], v[160:163], v[168:171], v[130:133]
	v_mfma_f32_16x16x32_bf16 v[118:121], v[146:149], v[176:179], v[118:121]
	v_mfma_f32_16x16x32_bf16 v[114:117], v[160:163], v[176:179], v[114:117]
	v_mfma_f32_16x16x32_bf16 v[102:105], v[146:149], v[206:209], v[102:105]
	v_mfma_f32_16x16x32_bf16 v[98:101], v[160:163], v[206:209], v[98:101]
	v_mfma_f32_16x16x32_bf16 v[86:89], v[146:149], v[220:223], v[86:89]
	v_mfma_f32_16x16x32_bf16 v[82:85], v[160:163], v[220:223], v[82:85]
	v_mfma_f32_16x16x32_bf16 v[134:137], v[156:159], v[172:175], v[134:137]
	v_mfma_f32_16x16x32_bf16 v[130:133], v[164:167], v[172:175], v[130:133]
	v_mfma_f32_16x16x32_bf16 v[118:121], v[156:159], v[202:205], v[118:121]
	v_mfma_f32_16x16x32_bf16 v[114:117], v[164:167], v[202:205], v[114:117]
	v_mfma_f32_16x16x32_bf16 v[102:105], v[156:159], v[216:219], v[102:105]
	v_mfma_f32_16x16x32_bf16 v[98:101], v[164:167], v[216:219], v[98:101]
	v_mfma_f32_16x16x32_bf16 v[86:89], v[156:159], v[224:227], v[86:89]
	v_mfma_f32_16x16x32_bf16 v[82:85], v[164:167], v[224:227], v[82:85]
	s_setprio 0
	s_barrier
	ds_read_b128 v[168:171], v155 offset:16384
	ds_read_b128 v[172:175], v155 offset:17408
	ds_read_b128 v[176:179], v155 offset:18432
	ds_read_b128 v[202:205], v155 offset:19456
	ds_read_b128 v[206:209], v155 offset:20480
	ds_read_b128 v[216:219], v155 offset:21504
	ds_read_b128 v[220:223], v155 offset:22528
	ds_read_b128 v[224:227], v155 offset:23552
	s_mov_b32 s25, m0
	s_mov_b32 m0, s78
	s_nop 0
	global_load_lds_dwordx4 v151, s[66:67]
	s_mov_b32 m0, s79
	s_nop 0
	global_load_lds_dwordx4 v153, s[66:67]
	s_mov_b32 m0, s25
	s_nop 0
	s_mov_b32 s25, m0
	s_mov_b32 m0, s80
	s_nop 0
	global_load_lds_dwordx4 v151, s[68:69]
	s_mov_b32 m0, s81
	s_nop 0
	global_load_lds_dwordx4 v153, s[68:69]
	s_mov_b32 m0, s25
	s_nop 0
	s_mov_b32 s25, m0
	s_mov_b32 m0, s75
	s_nop 0
	global_load_lds_dwordx4 v150, s[64:65]
	s_mov_b32 m0, s82
	s_nop 0
	global_load_lds_dwordx4 v152, s[64:65]
	s_mov_b32 m0, s25
	s_waitcnt vmcnt(8)
	s_waitcnt lgkmcnt(0)
	s_barrier
	s_setprio 1
	v_mfma_f32_16x16x32_bf16 v[78:81], v[38:41], v[168:171], v[78:81]
	v_mfma_f32_16x16x32_bf16 v[74:77], v[50:53], v[168:171], v[74:77]
	v_mfma_f32_16x16x32_bf16 v[62:65], v[38:41], v[176:179], v[62:65]
	v_mfma_f32_16x16x32_bf16 v[58:61], v[50:53], v[176:179], v[58:61]
	v_mfma_f32_16x16x32_bf16 v[30:33], v[38:41], v[206:209], v[30:33]
	v_mfma_f32_16x16x32_bf16 v[26:29], v[50:53], v[206:209], v[26:29]
	v_mfma_f32_16x16x32_bf16 v[14:17], v[38:41], v[220:223], v[14:17]
	v_mfma_f32_16x16x32_bf16 v[10:13], v[50:53], v[220:223], v[10:13]
	v_mfma_f32_16x16x32_bf16 v[78:81], v[42:45], v[172:175], v[78:81]
	v_mfma_f32_16x16x32_bf16 v[74:77], v[54:57], v[172:175], v[74:77]
	v_mfma_f32_16x16x32_bf16 v[62:65], v[42:45], v[202:205], v[62:65]
	v_mfma_f32_16x16x32_bf16 v[58:61], v[54:57], v[202:205], v[58:61]
	v_mfma_f32_16x16x32_bf16 v[30:33], v[42:45], v[216:219], v[30:33]
	v_mfma_f32_16x16x32_bf16 v[26:29], v[54:57], v[216:219], v[26:29]
	v_mfma_f32_16x16x32_bf16 v[14:17], v[42:45], v[224:227], v[14:17]
	v_mfma_f32_16x16x32_bf16 v[10:13], v[54:57], v[224:227], v[10:13]
	v_mfma_f32_16x16x32_bf16 v[46:49], v[146:149], v[176:179], v[46:49]
	v_mfma_f32_16x16x32_bf16 v[34:37], v[160:163], v[176:179], v[34:37]
	v_mfma_f32_16x16x32_bf16 v[22:25], v[146:149], v[206:209], v[22:25]
	v_mfma_f32_16x16x32_bf16 v[18:21], v[160:163], v[206:209], v[18:21]
	v_mfma_f32_16x16x32_bf16 v[6:9], v[146:149], v[220:223], v[6:9]
	v_mfma_f32_16x16x32_bf16 v[2:5], v[160:163], v[220:223], v[2:5]
	v_mfma_f32_16x16x32_bf16 v[38:41], v[146:149], v[168:171], v[70:73]
	v_mfma_f32_16x16x32_bf16 v[42:45], v[160:163], v[168:171], v[66:69]
	v_mfma_f32_16x16x32_bf16 v[46:49], v[156:159], v[202:205], v[46:49]
	v_mfma_f32_16x16x32_bf16 v[34:37], v[164:167], v[202:205], v[34:37]
	v_mfma_f32_16x16x32_bf16 v[22:25], v[156:159], v[216:219], v[22:25]
	v_mfma_f32_16x16x32_bf16 v[18:21], v[164:167], v[216:219], v[18:21]
	v_mfma_f32_16x16x32_bf16 v[6:9], v[156:159], v[224:227], v[6:9]
	v_mfma_f32_16x16x32_bf16 v[2:5], v[164:167], v[224:227], v[2:5]
	v_mfma_f32_16x16x32_bf16 v[38:41], v[156:159], v[172:175], v[38:41]
	v_mfma_f32_16x16x32_bf16 v[42:45], v[164:167], v[172:175], v[42:45]
	s_setprio 0
	s_barrier
	v_add_u32_e32 v0, 0x18000, v154
	ds_read_b128 v[50:53], v0
	ds_read_b128 v[54:57], v0 offset:1024
	ds_read_b128 v[66:69], v0 offset:2048
	ds_read_b128 v[70:73], v0 offset:3072
	v_add_u32_e32 v0, 0x1c000, v154
	ds_read_b128 v[146:149], v0
	ds_read_b128 v[156:159], v0 offset:1024
	ds_read_b128 v[160:163], v0 offset:2048
	ds_read_b128 v[164:167], v0 offset:3072
	ds_read_b128 v[168:171], v155 offset:32768
	ds_read_b128 v[172:175], v155 offset:33792
	ds_read_b128 v[176:179], v155 offset:34816
	ds_read_b128 v[202:205], v155 offset:35840
	ds_read_b128 v[206:209], v155 offset:36864
	ds_read_b128 v[216:219], v155 offset:37888
	ds_read_b128 v[220:223], v155 offset:38912
	ds_read_b128 v[224:227], v155 offset:39936
	s_mov_b32 s25, m0
	s_mov_b32 m0, s83
	s_nop 0
	global_load_lds_dwordx4 v150, s[62:63]
	s_mov_b32 m0, s84
	s_nop 0
	global_load_lds_dwordx4 v152, s[62:63]
	s_mov_b32 m0, s25
	s_waitcnt vmcnt(8)
	s_waitcnt lgkmcnt(0)
	s_barrier
	s_setprio 1
	v_mfma_f32_16x16x32_bf16 v[142:145], v[50:53], v[168:171], v[142:145]
	v_mfma_f32_16x16x32_bf16 v[138:141], v[66:69], v[168:171], v[138:141]
	v_mfma_f32_16x16x32_bf16 v[126:129], v[50:53], v[176:179], v[126:129]
	v_mfma_f32_16x16x32_bf16 v[122:125], v[66:69], v[176:179], v[122:125]
	v_mfma_f32_16x16x32_bf16 v[110:113], v[50:53], v[206:209], v[110:113]
	v_mfma_f32_16x16x32_bf16 v[106:109], v[66:69], v[206:209], v[106:109]
	v_mfma_f32_16x16x32_bf16 v[94:97], v[50:53], v[220:223], v[94:97]
	v_mfma_f32_16x16x32_bf16 v[90:93], v[66:69], v[220:223], v[90:93]
	v_mfma_f32_16x16x32_bf16 v[142:145], v[54:57], v[172:175], v[142:145]
	v_mfma_f32_16x16x32_bf16 v[138:141], v[70:73], v[172:175], v[138:141]
	v_mfma_f32_16x16x32_bf16 v[126:129], v[54:57], v[202:205], v[126:129]
	v_mfma_f32_16x16x32_bf16 v[122:125], v[70:73], v[202:205], v[122:125]
	v_mfma_f32_16x16x32_bf16 v[110:113], v[54:57], v[216:219], v[110:113]
	v_mfma_f32_16x16x32_bf16 v[106:109], v[70:73], v[216:219], v[106:109]
	v_mfma_f32_16x16x32_bf16 v[94:97], v[54:57], v[224:227], v[94:97]
	v_mfma_f32_16x16x32_bf16 v[90:93], v[70:73], v[224:227], v[90:93]
	v_mfma_f32_16x16x32_bf16 v[134:137], v[146:149], v[168:171], v[134:137]
	v_mfma_f32_16x16x32_bf16 v[130:133], v[160:163], v[168:171], v[130:133]
	v_mfma_f32_16x16x32_bf16 v[118:121], v[146:149], v[176:179], v[118:121]
	v_mfma_f32_16x16x32_bf16 v[114:117], v[160:163], v[176:179], v[114:117]
	v_mfma_f32_16x16x32_bf16 v[102:105], v[146:149], v[206:209], v[102:105]
	v_mfma_f32_16x16x32_bf16 v[98:101], v[160:163], v[206:209], v[98:101]
	v_mfma_f32_16x16x32_bf16 v[86:89], v[146:149], v[220:223], v[86:89]
	v_mfma_f32_16x16x32_bf16 v[82:85], v[160:163], v[220:223], v[82:85]
	v_mfma_f32_16x16x32_bf16 v[134:137], v[156:159], v[172:175], v[134:137]
	v_mfma_f32_16x16x32_bf16 v[130:133], v[164:167], v[172:175], v[130:133]
	v_mfma_f32_16x16x32_bf16 v[118:121], v[156:159], v[202:205], v[118:121]
	v_mfma_f32_16x16x32_bf16 v[114:117], v[164:167], v[202:205], v[114:117]
	v_mfma_f32_16x16x32_bf16 v[102:105], v[156:159], v[216:219], v[102:105]
	v_mfma_f32_16x16x32_bf16 v[98:101], v[164:167], v[216:219], v[98:101]
	v_mfma_f32_16x16x32_bf16 v[86:89], v[156:159], v[224:227], v[86:89]
	v_mfma_f32_16x16x32_bf16 v[82:85], v[164:167], v[224:227], v[82:85]
	s_setprio 0
	s_barrier
	ds_read_b128 v[168:171], v155 offset:49152
	ds_read_b128 v[172:175], v155 offset:50176
	ds_read_b128 v[176:179], v155 offset:51200
	ds_read_b128 v[202:205], v155 offset:52224
	ds_read_b128 v[206:209], v155 offset:53248
	ds_read_b128 v[216:219], v155 offset:54272
	ds_read_b128 v[220:223], v155 offset:55296
	ds_read_b128 v[224:227], v155 offset:56320
	s_mov_b32 s25, m0
	s_mov_b32 m0, s87
	s_nop 0
	global_load_lds_dwordx4 v151, s[60:61]
	s_mov_b32 m0, s88
	s_nop 0
	global_load_lds_dwordx4 v153, s[60:61]
	s_mov_b32 m0, s25
	s_nop 0
	s_mov_b32 s25, m0
	s_mov_b32 m0, s91
	s_nop 0
	global_load_lds_dwordx4 v151, s[56:57]
	s_mov_b32 m0, s97
	s_nop 0
	global_load_lds_dwordx4 v153, s[56:57]
	s_mov_b32 m0, s25
	s_nop 0
	s_mov_b32 s25, m0
	s_mov_b32 m0, s89
	s_nop 0
	global_load_lds_dwordx4 v150, s[58:59]
	s_mov_b32 m0, s90
	s_nop 0
	global_load_lds_dwordx4 v152, s[58:59]
	s_mov_b32 m0, s25
	s_waitcnt vmcnt(8)
	s_waitcnt lgkmcnt(0)
	s_barrier
	s_setprio 1
	v_mfma_f32_16x16x32_bf16 v[78:81], v[50:53], v[168:171], v[78:81]
	v_mfma_f32_16x16x32_bf16 v[74:77], v[66:69], v[168:171], v[74:77]
	v_mfma_f32_16x16x32_bf16 v[62:65], v[50:53], v[176:179], v[62:65]
	v_mfma_f32_16x16x32_bf16 v[58:61], v[66:69], v[176:179], v[58:61]
	v_mfma_f32_16x16x32_bf16 v[30:33], v[50:53], v[206:209], v[30:33]
	v_mfma_f32_16x16x32_bf16 v[26:29], v[66:69], v[206:209], v[26:29]
	v_mfma_f32_16x16x32_bf16 v[14:17], v[50:53], v[220:223], v[14:17]
	v_mfma_f32_16x16x32_bf16 v[10:13], v[66:69], v[220:223], v[10:13]
	v_mfma_f32_16x16x32_bf16 v[78:81], v[54:57], v[172:175], v[78:81]
	v_mfma_f32_16x16x32_bf16 v[74:77], v[70:73], v[172:175], v[74:77]
	v_mfma_f32_16x16x32_bf16 v[62:65], v[54:57], v[202:205], v[62:65]
	v_mfma_f32_16x16x32_bf16 v[58:61], v[70:73], v[202:205], v[58:61]
	v_mfma_f32_16x16x32_bf16 v[30:33], v[54:57], v[216:219], v[30:33]
	v_mfma_f32_16x16x32_bf16 v[26:29], v[70:73], v[216:219], v[26:29]
	v_mfma_f32_16x16x32_bf16 v[14:17], v[54:57], v[224:227], v[14:17]
	v_mfma_f32_16x16x32_bf16 v[10:13], v[70:73], v[224:227], v[10:13]
	v_mfma_f32_16x16x32_bf16 v[38:41], v[146:149], v[168:171], v[38:41]
	v_mfma_f32_16x16x32_bf16 v[70:73], v[156:159], v[172:175], v[38:41]
	v_mfma_f32_16x16x32_bf16 v[38:41], v[160:163], v[168:171], v[42:45]
	v_mfma_f32_16x16x32_bf16 v[66:69], v[164:167], v[172:175], v[38:41]
	v_mfma_f32_16x16x32_bf16 v[38:41], v[146:149], v[176:179], v[46:49]
	v_mfma_f32_16x16x32_bf16 v[34:37], v[160:163], v[176:179], v[34:37]
	v_mfma_f32_16x16x32_bf16 v[22:25], v[146:149], v[206:209], v[22:25]
	v_mfma_f32_16x16x32_bf16 v[18:21], v[160:163], v[206:209], v[18:21]
	v_mfma_f32_16x16x32_bf16 v[6:9], v[146:149], v[220:223], v[6:9]
	v_mfma_f32_16x16x32_bf16 v[2:5], v[160:163], v[220:223], v[2:5]
	v_mfma_f32_16x16x32_bf16 v[46:49], v[156:159], v[202:205], v[38:41]
	v_mfma_f32_16x16x32_bf16 v[34:37], v[164:167], v[202:205], v[34:37]
	v_mfma_f32_16x16x32_bf16 v[22:25], v[156:159], v[216:219], v[22:25]
	v_mfma_f32_16x16x32_bf16 v[18:21], v[164:167], v[216:219], v[18:21]
	v_mfma_f32_16x16x32_bf16 v[6:9], v[156:159], v[224:227], v[6:9]
	v_mfma_f32_16x16x32_bf16 v[2:5], v[164:167], v[224:227], v[2:5]
	s_setprio 0
	s_barrier
	s_movk_i32 s25, 0x100
	s_andn2_b64 vcc, exec, s[40:41]
	s_mov_b64 s[56:57], -1
	s_mov_b64 s[40:41], 0
	s_cbranch_vccz .LBB0_372
	s_and_b64 vcc, exec, s[50:51]
	s_cbranch_vccz .LBB0_375
	s_barrier

.LBB0_439:
	v_add_u32_e32 v0, 0x10000, v152
	ds_read_b128 v[2:5], v0
	ds_read_b128 v[6:9], v0 offset:1024
	ds_read_b128 v[10:13], v0 offset:2048
	ds_read_b128 v[14:17], v0 offset:3072
	v_add_u32_e32 v0, 0x14000, v152
	ds_read_b128 v[18:21], v0
	ds_read_b128 v[22:25], v0 offset:1024
	ds_read_b128 v[26:29], v0 offset:2048
	ds_read_b128 v[30:33], v0 offset:3072
	s_add_u32 s58, s58, s4
	s_addc_u32 s59, s59, s5
	s_add_u32 s40, s56, 0x80
	s_addc_u32 s41, s57, 0
	ds_read_b128 v[34:37], v153
	ds_read_b128 v[38:41], v153 offset:1024
	ds_read_b128 v[42:45], v153 offset:2048
	ds_read_b128 v[46:49], v153 offset:3072
	ds_read_b128 v[50:53], v153 offset:4096
	ds_read_b128 v[54:57], v153 offset:5120
	ds_read_b128 v[58:61], v153 offset:6144
	s_waitcnt vmcnt(0)
	ds_read_b128 v[62:65], v153 offset:7168
	s_add_u32 s58, s58, 0x80
	s_addc_u32 s59, s59, 0
	s_mov_b32 s75, m0
	s_mov_b32 m0, s67
	s_nop 0
	global_load_lds_dwordx4 v148, s[58:59]
	s_mov_b32 m0, s68
	s_nop 0
	global_load_lds_dwordx4 v150, s[58:59]
	s_mov_b32 m0, s75
	s_waitcnt vmcnt(8)
	s_waitcnt lgkmcnt(0)
	s_barrier
	s_setprio 1
	s_waitcnt lgkmcnt(0)
	v_mfma_f32_16x16x32_bf16 v[66:69], v[2:5], v[34:37], 0
	v_mfma_f32_16x16x32_bf16 v[70:73], v[10:13], v[34:37], 0
	v_mfma_f32_16x16x32_bf16 v[74:77], v[2:5], v[42:45], 0
	v_mfma_f32_16x16x32_bf16 v[78:81], v[10:13], v[42:45], 0
	s_waitcnt vmcnt(0)
	v_mfma_f32_16x16x32_bf16 v[82:85], v[2:5], v[50:53], 0
	v_mfma_f32_16x16x32_bf16 v[86:89], v[10:13], v[50:53], 0
	v_mfma_f32_16x16x32_bf16 v[90:93], v[2:5], v[58:61], 0
	v_mfma_f32_16x16x32_bf16 v[94:97], v[10:13], v[58:61], 0
	v_mfma_f32_16x16x32_bf16 v[66:69], v[6:9], v[38:41], v[66:69]
	v_mfma_f32_16x16x32_bf16 v[70:73], v[14:17], v[38:41], v[70:73]
	v_mfma_f32_16x16x32_bf16 v[74:77], v[6:9], v[46:49], v[74:77]
	v_mfma_f32_16x16x32_bf16 v[78:81], v[14:17], v[46:49], v[78:81]
	v_mfma_f32_16x16x32_bf16 v[82:85], v[6:9], v[54:57], v[82:85]
	v_mfma_f32_16x16x32_bf16 v[86:89], v[14:17], v[54:57], v[86:89]
	v_mfma_f32_16x16x32_bf16 v[90:93], v[6:9], v[62:65], v[90:93]
	v_mfma_f32_16x16x32_bf16 v[98:101], v[14:17], v[62:65], v[94:97]
	v_mfma_f32_16x16x32_bf16 v[94:97], v[18:21], v[34:37], 0
	v_mfma_f32_16x16x32_bf16 v[34:37], v[26:29], v[34:37], 0
	v_mfma_f32_16x16x32_bf16 v[102:105], v[22:25], v[38:41], v[94:97]
	v_mfma_f32_16x16x32_bf16 v[34:37], v[30:33], v[38:41], v[34:37]
	v_mfma_f32_16x16x32_bf16 v[38:41], v[18:21], v[42:45], 0
	v_mfma_f32_16x16x32_bf16 v[42:45], v[26:29], v[42:45], 0
	v_mfma_f32_16x16x32_bf16 v[38:41], v[22:25], v[46:49], v[38:41]
	v_mfma_f32_16x16x32_bf16 v[42:45], v[30:33], v[46:49], v[42:45]
	v_mfma_f32_16x16x32_bf16 v[46:49], v[18:21], v[50:53], 0
	v_mfma_f32_16x16x32_bf16 v[50:53], v[26:29], v[50:53], 0
	v_mfma_f32_16x16x32_bf16 v[46:49], v[22:25], v[54:57], v[46:49]
	v_mfma_f32_16x16x32_bf16 v[50:53], v[30:33], v[54:57], v[50:53]
	v_mfma_f32_16x16x32_bf16 v[54:57], v[18:21], v[58:61], 0
	v_mfma_f32_16x16x32_bf16 v[58:61], v[26:29], v[58:61], 0
	v_mfma_f32_16x16x32_bf16 v[54:57], v[22:25], v[62:65], v[54:57]
	v_mfma_f32_16x16x32_bf16 v[58:61], v[30:33], v[62:65], v[58:61]
	s_setprio 0
	s_barrier
	ds_read_b128 v[62:65], v153 offset:16384
	ds_read_b128 v[94:97], v153 offset:17408
	ds_read_b128 v[106:109], v153 offset:18432
	ds_read_b128 v[110:113], v153 offset:19456
	ds_read_b128 v[114:117], v153 offset:20480
	ds_read_b128 v[118:121], v153 offset:21504
	ds_read_b128 v[122:125], v153 offset:22528
	ds_read_b128 v[126:129], v153 offset:23552
	s_mov_b32 s58, m0
	s_mov_b32 m0, s25
	s_nop 0
	global_load_lds_dwordx4 v149, s[42:43]
	s_mov_b32 m0, s26
	s_nop 0
	global_load_lds_dwordx4 v151, s[42:43]
	s_mov_b32 m0, s58
	s_add_u32 s58, s42, s20
	s_addc_u32 s59, s43, s21
	s_mov_b32 s75, m0
	s_mov_b32 m0, s27
	s_nop 0
	global_load_lds_dwordx4 v149, s[58:59]
	s_mov_b32 m0, s28
	s_nop 0
	global_load_lds_dwordx4 v151, s[58:59]
	s_mov_b32 m0, s75
	s_nop 0
	s_mov_b32 s75, m0
	s_mov_b32 m0, s24
	s_nop 0
	global_load_lds_dwordx4 v148, s[56:57]
	s_mov_b32 m0, s29
	s_nop 0
	global_load_lds_dwordx4 v150, s[56:57]
	s_mov_b32 m0, s75
	s_waitcnt vmcnt(8)
	s_waitcnt lgkmcnt(0)
	s_barrier
	s_setprio 1
	v_mfma_f32_16x16x32_bf16 v[130:133], v[2:5], v[62:65], 0
	v_mfma_f32_16x16x32_bf16 v[154:157], v[6:9], v[94:97], v[130:133]
	v_mfma_f32_16x16x32_bf16 v[130:133], v[10:13], v[62:65], 0
	v_mfma_f32_16x16x32_bf16 v[158:161], v[14:17], v[94:97], v[130:133]
	v_mfma_f32_16x16x32_bf16 v[130:133], v[2:5], v[106:109], 0
	v_mfma_f32_16x16x32_bf16 v[162:165], v[6:9], v[110:113], v[130:133]
	v_mfma_f32_16x16x32_bf16 v[130:133], v[10:13], v[106:109], 0
	v_mfma_f32_16x16x32_bf16 v[166:169], v[14:17], v[110:113], v[130:133]
	v_mfma_f32_16x16x32_bf16 v[130:133], v[2:5], v[114:117], 0
	v_mfma_f32_16x16x32_bf16 v[2:5], v[2:5], v[122:125], 0
	v_mfma_f32_16x16x32_bf16 v[170:173], v[6:9], v[118:121], v[130:133]
	v_mfma_f32_16x16x32_bf16 v[2:5], v[6:9], v[126:129], v[2:5]
	v_mfma_f32_16x16x32_bf16 v[6:9], v[10:13], v[122:125], 0
	v_mfma_f32_16x16x32_bf16 v[130:133], v[10:13], v[114:117], 0
	v_mfma_f32_16x16x32_bf16 v[6:9], v[14:17], v[126:129], v[6:9]
	v_mfma_f32_16x16x32_bf16 v[174:177], v[14:17], v[118:121], v[130:133]
	v_mfma_f32_16x16x32_bf16 v[10:13], v[18:21], v[62:65], 0
	v_mfma_f32_16x16x32_bf16 v[202:205], v[22:25], v[94:97], v[10:13]
	v_mfma_f32_16x16x32_bf16 v[10:13], v[26:29], v[62:65], 0
	v_mfma_f32_16x16x32_bf16 v[206:209], v[30:33], v[94:97], v[10:13]
	v_mfma_f32_16x16x32_bf16 v[10:13], v[18:21], v[106:109], 0
	v_mfma_f32_16x16x32_bf16 v[216:219], v[22:25], v[110:113], v[10:13]
	v_mfma_f32_16x16x32_bf16 v[10:13], v[26:29], v[106:109], 0
	v_mfma_f32_16x16x32_bf16 v[220:223], v[30:33], v[110:113], v[10:13]
	v_mfma_f32_16x16x32_bf16 v[10:13], v[18:21], v[114:117], 0
	v_mfma_f32_16x16x32_bf16 v[224:227], v[22:25], v[118:121], v[10:13]
	v_mfma_f32_16x16x32_bf16 v[10:13], v[26:29], v[114:117], 0
	v_mfma_f32_16x16x32_bf16 v[228:231], v[30:33], v[118:121], v[10:13]
	v_mfma_f32_16x16x32_bf16 v[10:13], v[18:21], v[122:125], 0
	v_mfma_f32_16x16x32_bf16 v[18:21], v[22:25], v[126:129], v[10:13]
	v_mfma_f32_16x16x32_bf16 v[10:13], v[26:29], v[122:125], 0
	v_mfma_f32_16x16x32_bf16 v[22:25], v[30:33], v[126:129], v[10:13]
	s_setprio 0
	s_barrier
	v_add_u32_e32 v0, 0x18000, v152
	s_nop 3
	ds_read_b128 v[10:13], v0
	ds_read_b128 v[14:17], v0 offset:1024
	ds_read_b128 v[26:29], v0 offset:2048
	ds_read_b128 v[30:33], v0 offset:3072
	v_add_u32_e32 v0, 0x1c000, v152
	ds_read_b128 v[232:235], v0
	ds_read_b128 v[236:239], v0 offset:1024
	ds_read_b128 v[240:243], v0 offset:2048
	ds_read_b128 v[244:247], v0 offset:3072
	ds_read_b128 v[62:65], v153 offset:32768
	ds_read_b128 v[114:117], v153 offset:33792
	ds_read_b128 v[198:201], v153 offset:34816
	ds_read_b128 v[182:185], v153 offset:35840
	ds_read_b128 v[190:193], v153 offset:36864
	ds_read_b128 v[194:197], v153 offset:37888
	ds_read_b128 v[186:189], v153 offset:38912
	ds_read_b128 v[178:181], v153 offset:39936
	s_add_u32 s78, s56, s4
	s_addc_u32 s79, s57, s5
	s_mov_b32 s75, m0
	s_mov_b32 m0, s30
	s_nop 0
	global_load_lds_dwordx4 v148, s[78:79]
	s_mov_b32 m0, s31
	s_nop 0
	global_load_lds_dwordx4 v150, s[78:79]
	s_mov_b32 m0, s75
	s_waitcnt vmcnt(8)
	s_waitcnt lgkmcnt(0)
	s_barrier
	s_setprio 1
	v_mfma_f32_16x16x32_bf16 v[66:69], v[10:13], v[62:65], v[66:69]
	v_mfma_f32_16x16x32_bf16 v[142:145], v[14:17], v[114:117], v[66:69]
	v_mfma_f32_16x16x32_bf16 v[66:69], v[26:29], v[62:65], v[70:73]
	v_mfma_f32_16x16x32_bf16 v[138:141], v[30:33], v[114:117], v[66:69]
	v_mfma_f32_16x16x32_bf16 v[66:69], v[10:13], v[198:201], v[74:77]
	v_mfma_f32_16x16x32_bf16 v[126:129], v[14:17], v[182:185], v[66:69]
	v_mfma_f32_16x16x32_bf16 v[66:69], v[26:29], v[198:201], v[78:81]
	v_mfma_f32_16x16x32_bf16 v[122:125], v[30:33], v[182:185], v[66:69]
	v_mfma_f32_16x16x32_bf16 v[66:69], v[10:13], v[190:193], v[82:85]
	v_mfma_f32_16x16x32_bf16 v[110:113], v[14:17], v[194:197], v[66:69]
	v_mfma_f32_16x16x32_bf16 v[66:69], v[26:29], v[190:193], v[86:89]
	v_mfma_f32_16x16x32_bf16 v[106:109], v[30:33], v[194:197], v[66:69]
	v_mfma_f32_16x16x32_bf16 v[66:69], v[10:13], v[186:189], v[90:93]
	v_mfma_f32_16x16x32_bf16 v[94:97], v[14:17], v[178:181], v[66:69]
	v_mfma_f32_16x16x32_bf16 v[66:69], v[26:29], v[186:189], v[98:101]
	v_mfma_f32_16x16x32_bf16 v[90:93], v[30:33], v[178:181], v[66:69]
	v_mfma_f32_16x16x32_bf16 v[34:37], v[240:243], v[62:65], v[34:37]
	v_mfma_f32_16x16x32_bf16 v[130:133], v[244:247], v[114:117], v[34:37]
	v_mfma_f32_16x16x32_bf16 v[34:37], v[232:235], v[198:201], v[38:41]
	v_mfma_f32_16x16x32_bf16 v[66:69], v[232:235], v[62:65], v[102:105]
	v_mfma_f32_16x16x32_bf16 v[118:121], v[236:239], v[182:185], v[34:37]
	v_mfma_f32_16x16x32_bf16 v[34:37], v[240:243], v[198:201], v[42:45]
	v_mfma_f32_16x16x32_bf16 v[134:137], v[236:239], v[114:117], v[66:69]
	v_mfma_f32_16x16x32_bf16 v[114:117], v[244:247], v[182:185], v[34:37]
	v_mfma_f32_16x16x32_bf16 v[34:37], v[232:235], v[190:193], v[46:49]
	v_mfma_f32_16x16x32_bf16 v[102:105], v[236:239], v[194:197], v[34:37]
	v_mfma_f32_16x16x32_bf16 v[34:37], v[240:243], v[190:193], v[50:53]
	v_mfma_f32_16x16x32_bf16 v[98:101], v[244:247], v[194:197], v[34:37]
	v_mfma_f32_16x16x32_bf16 v[34:37], v[232:235], v[186:189], v[54:57]
	v_mfma_f32_16x16x32_bf16 v[86:89], v[236:239], v[178:181], v[34:37]
	v_mfma_f32_16x16x32_bf16 v[34:37], v[240:243], v[186:189], v[58:61]
	v_mfma_f32_16x16x32_bf16 v[82:85], v[244:247], v[178:181], v[34:37]
	s_setprio 0
	s_barrier
	s_nop 4
	ds_read_b128 v[34:37], v153 offset:49152
	ds_read_b128 v[38:41], v153 offset:50176
	ds_read_b128 v[50:53], v153 offset:51200
	ds_read_b128 v[178:181], v153 offset:52224
	ds_read_b128 v[182:185], v153 offset:53248
	ds_read_b128 v[186:189], v153 offset:54272
	ds_read_b128 v[190:193], v153 offset:55296
	ds_read_b128 v[194:197], v153 offset:56320
	s_add_u32 s78, s42, 0x80
	s_addc_u32 s79, s43, 0
	s_mov_b32 s75, m0
	s_mov_b32 m0, s61
	s_nop 0
	global_load_lds_dwordx4 v149, s[78:79]
	s_mov_b32 m0, s62
	s_nop 0
	global_load_lds_dwordx4 v151, s[78:79]
	s_mov_b32 m0, s75
	s_add_u32 s58, s58, 0x80
	s_addc_u32 s59, s59, 0
	s_mov_b32 s75, m0
	s_mov_b32 m0, s65
	s_nop 0
	global_load_lds_dwordx4 v149, s[58:59]
	s_mov_b32 m0, s66
	s_nop 0
	global_load_lds_dwordx4 v151, s[58:59]
	s_mov_b32 m0, s75
	s_mov_b32 s58, m0
	s_mov_b32 m0, s63
	s_nop 0
	global_load_lds_dwordx4 v148, s[40:41]
	s_mov_b32 m0, s64
	s_nop 0
	global_load_lds_dwordx4 v150, s[40:41]
	s_mov_b32 m0, s58
	s_waitcnt vmcnt(8)
	s_waitcnt lgkmcnt(0)
	s_barrier
	s_setprio 1
	v_mfma_f32_16x16x32_bf16 v[42:45], v[10:13], v[34:37], v[154:157]
	v_mfma_f32_16x16x32_bf16 v[78:81], v[14:17], v[38:41], v[42:45]
	v_mfma_f32_16x16x32_bf16 v[42:45], v[26:29], v[34:37], v[158:161]
	v_mfma_f32_16x16x32_bf16 v[74:77], v[30:33], v[38:41], v[42:45]
	v_mfma_f32_16x16x32_bf16 v[42:45], v[10:13], v[50:53], v[162:165]
	v_mfma_f32_16x16x32_bf16 v[62:65], v[14:17], v[178:181], v[42:45]
	v_mfma_f32_16x16x32_bf16 v[42:45], v[26:29], v[50:53], v[166:169]
	v_mfma_f32_16x16x32_bf16 v[58:61], v[30:33], v[178:181], v[42:45]
	v_mfma_f32_16x16x32_bf16 v[42:45], v[10:13], v[182:185], v[170:173]
	v_mfma_f32_16x16x32_bf16 v[2:5], v[10:13], v[190:193], v[2:5]
	v_mfma_f32_16x16x32_bf16 v[46:49], v[14:17], v[186:189], v[42:45]
	v_mfma_f32_16x16x32_bf16 v[42:45], v[26:29], v[182:185], v[174:177]
	v_mfma_f32_16x16x32_bf16 v[14:17], v[14:17], v[194:197], v[2:5]
	v_mfma_f32_16x16x32_bf16 v[2:5], v[26:29], v[190:193], v[6:9]
	v_mfma_f32_16x16x32_bf16 v[42:45], v[30:33], v[186:189], v[42:45]
	v_mfma_f32_16x16x32_bf16 v[10:13], v[30:33], v[194:197], v[2:5]
	v_mfma_f32_16x16x32_bf16 v[2:5], v[232:235], v[34:37], v[202:205]
	v_mfma_f32_16x16x32_bf16 v[70:73], v[236:239], v[38:41], v[2:5]
	v_mfma_f32_16x16x32_bf16 v[2:5], v[240:243], v[34:37], v[206:209]
	v_mfma_f32_16x16x32_bf16 v[66:69], v[244:247], v[38:41], v[2:5]
	v_mfma_f32_16x16x32_bf16 v[2:5], v[232:235], v[50:53], v[216:219]
	v_mfma_f32_16x16x32_bf16 v[54:57], v[236:239], v[178:181], v[2:5]
	v_mfma_f32_16x16x32_bf16 v[2:5], v[240:243], v[50:53], v[220:223]
	v_mfma_f32_16x16x32_bf16 v[50:53], v[244:247], v[178:181], v[2:5]
	v_mfma_f32_16x16x32_bf16 v[2:5], v[232:235], v[182:185], v[224:227]
	v_mfma_f32_16x16x32_bf16 v[38:41], v[236:239], v[186:189], v[2:5]
	v_mfma_f32_16x16x32_bf16 v[2:5], v[240:243], v[182:185], v[228:231]
	v_mfma_f32_16x16x32_bf16 v[34:37], v[244:247], v[186:189], v[2:5]
	v_mfma_f32_16x16x32_bf16 v[2:5], v[232:235], v[190:193], v[18:21]
	v_mfma_f32_16x16x32_bf16 v[6:9], v[236:239], v[194:197], v[2:5]
	v_mfma_f32_16x16x32_bf16 v[2:5], v[240:243], v[190:193], v[22:25]
	v_mfma_f32_16x16x32_bf16 v[2:5], v[244:247], v[194:197], v[2:5]
	s_setprio 0
	s_barrier
	s_andn2_b64 vcc, exec, s[48:49]
	s_cbranch_vccnz .LBB0_441
	s_barrier

.LBB0_484:
	v_add_u32_e32 v0, 0x10000, v156
	ds_read_b128 v[62:65], v0
	ds_read_b128 v[66:69], v0 offset:1024
	ds_read_b128 v[70:73], v0 offset:2048
	ds_read_b128 v[74:77], v0 offset:3072
	v_add_u32_e32 v0, 0x14000, v156
	ds_read_b128 v[146:149], v0
	ds_read_b128 v[158:161], v0 offset:1024
	ds_read_b128 v[162:165], v0 offset:2048
	ds_read_b128 v[166:169], v0 offset:3072
	s_cmp_eq_u32 s26, 12
	s_cselect_b32 s44, s70, s24
	s_cselect_b32 s45, s71, s25
	s_cselect_b32 s42, s72, s0
	s_cselect_b32 s43, s73, s11
	s_add_u32 s40, s44, 0x80
	s_addc_u32 s41, s45, 0
	ds_read_b128 v[170:173], v157
	ds_read_b128 v[174:177], v157 offset:1024
	ds_read_b128 v[202:205], v157 offset:2048
	ds_read_b128 v[206:209], v157 offset:3072
	ds_read_b128 v[216:219], v157 offset:4096
	ds_read_b128 v[220:223], v157 offset:5120
	ds_read_b128 v[224:227], v157 offset:6144
	ds_read_b128 v[228:231], v157 offset:7168
	s_add_u32 s27, s24, s52
	s_addc_u32 s29, s25, s53
	s_add_u32 s28, s27, 0xffffff80
	s_addc_u32 s29, s29, -1
	s_mov_b32 s27, m0
	s_mov_b32 m0, s68
	s_nop 0
	global_load_lds_dwordx4 v152, s[28:29]
	s_mov_b32 m0, s69
	s_nop 0
	global_load_lds_dwordx4 v154, s[28:29]
	s_mov_b32 m0, s27
	s_waitcnt vmcnt(8)
	s_waitcnt lgkmcnt(0)
	s_barrier
	s_setprio 1
	v_mfma_f32_16x16x32_bf16 v[142:145], v[62:65], v[170:173], v[142:145]
	v_mfma_f32_16x16x32_bf16 v[138:141], v[70:73], v[170:173], v[138:141]
	v_mfma_f32_16x16x32_bf16 v[126:129], v[62:65], v[202:205], v[126:129]
	v_mfma_f32_16x16x32_bf16 v[122:125], v[70:73], v[202:205], v[122:125]
	v_mfma_f32_16x16x32_bf16 v[110:113], v[62:65], v[216:219], v[110:113]
	v_mfma_f32_16x16x32_bf16 v[106:109], v[70:73], v[216:219], v[106:109]
	v_mfma_f32_16x16x32_bf16 v[94:97], v[62:65], v[224:227], v[94:97]
	v_mfma_f32_16x16x32_bf16 v[90:93], v[70:73], v[224:227], v[90:93]
	v_mfma_f32_16x16x32_bf16 v[142:145], v[66:69], v[174:177], v[142:145]
	v_mfma_f32_16x16x32_bf16 v[138:141], v[74:77], v[174:177], v[138:141]
	v_mfma_f32_16x16x32_bf16 v[126:129], v[66:69], v[206:209], v[126:129]
	v_mfma_f32_16x16x32_bf16 v[122:125], v[74:77], v[206:209], v[122:125]
	v_mfma_f32_16x16x32_bf16 v[110:113], v[66:69], v[220:223], v[110:113]
	v_mfma_f32_16x16x32_bf16 v[106:109], v[74:77], v[220:223], v[106:109]
	v_mfma_f32_16x16x32_bf16 v[94:97], v[66:69], v[228:231], v[94:97]
	v_mfma_f32_16x16x32_bf16 v[90:93], v[74:77], v[228:231], v[90:93]
	v_mfma_f32_16x16x32_bf16 v[134:137], v[146:149], v[170:173], v[134:137]
	v_mfma_f32_16x16x32_bf16 v[130:133], v[162:165], v[170:173], v[130:133]
	v_mfma_f32_16x16x32_bf16 v[118:121], v[146:149], v[202:205], v[118:121]
	v_mfma_f32_16x16x32_bf16 v[114:117], v[162:165], v[202:205], v[114:117]
	v_mfma_f32_16x16x32_bf16 v[102:105], v[146:149], v[216:219], v[102:105]
	v_mfma_f32_16x16x32_bf16 v[98:101], v[162:165], v[216:219], v[98:101]
	v_mfma_f32_16x16x32_bf16 v[86:89], v[146:149], v[224:227], v[86:89]
	v_mfma_f32_16x16x32_bf16 v[82:85], v[162:165], v[224:227], v[82:85]
	v_mfma_f32_16x16x32_bf16 v[134:137], v[158:161], v[174:177], v[134:137]
	v_mfma_f32_16x16x32_bf16 v[130:133], v[166:169], v[174:177], v[130:133]
	v_mfma_f32_16x16x32_bf16 v[118:121], v[158:161], v[206:209], v[118:121]
	v_mfma_f32_16x16x32_bf16 v[114:117], v[166:169], v[206:209], v[114:117]
	v_mfma_f32_16x16x32_bf16 v[102:105], v[158:161], v[220:223], v[102:105]
	v_mfma_f32_16x16x32_bf16 v[98:101], v[166:169], v[220:223], v[98:101]
	v_mfma_f32_16x16x32_bf16 v[86:89], v[158:161], v[228:231], v[86:89]
	v_mfma_f32_16x16x32_bf16 v[82:85], v[166:169], v[228:231], v[82:85]
	s_setprio 0
	s_barrier
	ds_read_b128 v[170:173], v157 offset:16384
	ds_read_b128 v[174:177], v157 offset:17408
	ds_read_b128 v[202:205], v157 offset:18432
	ds_read_b128 v[206:209], v157 offset:19456
	ds_read_b128 v[216:219], v157 offset:20480
	ds_read_b128 v[220:223], v157 offset:21504
	ds_read_b128 v[224:227], v157 offset:22528
	ds_read_b128 v[228:231], v157 offset:23552
	s_mov_b32 s27, m0
	s_mov_b32 m0, s65
	s_nop 0
	global_load_lds_dwordx4 v153, s[42:43]
	s_mov_b32 m0, s22
	s_nop 0
	global_load_lds_dwordx4 v155, s[42:43]
	s_mov_b32 m0, s27
	s_add_u32 s46, s42, s56
	s_addc_u32 s47, s43, s57
	s_mov_b32 s27, m0
	s_mov_b32 m0, s23
	s_nop 0
	global_load_lds_dwordx4 v153, s[46:47]
	s_mov_b32 m0, s50
	s_nop 0
	global_load_lds_dwordx4 v155, s[46:47]
	s_mov_b32 m0, s27
	s_nop 0
	s_mov_b32 s27, m0
	s_mov_b32 m0, s64
	s_nop 0
	global_load_lds_dwordx4 v152, s[44:45]
	s_mov_b32 m0, s51
	s_nop 0
	global_load_lds_dwordx4 v154, s[44:45]
	s_mov_b32 m0, s27
	s_waitcnt vmcnt(8)
	s_waitcnt lgkmcnt(0)
	s_barrier
	s_setprio 1
	v_mfma_f32_16x16x32_bf16 v[78:81], v[62:65], v[170:173], v[78:81]
	v_mfma_f32_16x16x32_bf16 v[58:61], v[70:73], v[170:173], v[58:61]
	v_mfma_f32_16x16x32_bf16 v[46:49], v[62:65], v[202:205], v[46:49]
	v_mfma_f32_16x16x32_bf16 v[42:45], v[70:73], v[202:205], v[42:45]
	v_mfma_f32_16x16x32_bf16 v[30:33], v[62:65], v[216:219], v[30:33]
	v_mfma_f32_16x16x32_bf16 v[26:29], v[70:73], v[216:219], v[26:29]
	v_mfma_f32_16x16x32_bf16 v[14:17], v[62:65], v[224:227], v[14:17]
	v_mfma_f32_16x16x32_bf16 v[10:13], v[70:73], v[224:227], v[10:13]
	v_mfma_f32_16x16x32_bf16 v[78:81], v[66:69], v[174:177], v[78:81]
	v_mfma_f32_16x16x32_bf16 v[58:61], v[74:77], v[174:177], v[58:61]
	v_mfma_f32_16x16x32_bf16 v[46:49], v[66:69], v[206:209], v[46:49]
	v_mfma_f32_16x16x32_bf16 v[42:45], v[74:77], v[206:209], v[42:45]
	v_mfma_f32_16x16x32_bf16 v[30:33], v[66:69], v[220:223], v[30:33]
	v_mfma_f32_16x16x32_bf16 v[26:29], v[74:77], v[220:223], v[26:29]
	v_mfma_f32_16x16x32_bf16 v[14:17], v[66:69], v[228:231], v[14:17]
	v_mfma_f32_16x16x32_bf16 v[10:13], v[74:77], v[228:231], v[10:13]
	v_mfma_f32_16x16x32_bf16 v[54:57], v[146:149], v[170:173], v[54:57]
	v_mfma_f32_16x16x32_bf16 v[50:53], v[162:165], v[170:173], v[50:53]
	v_mfma_f32_16x16x32_bf16 v[38:41], v[146:149], v[202:205], v[38:41]
	v_mfma_f32_16x16x32_bf16 v[34:37], v[162:165], v[202:205], v[34:37]
	v_mfma_f32_16x16x32_bf16 v[22:25], v[146:149], v[216:219], v[22:25]
	v_mfma_f32_16x16x32_bf16 v[18:21], v[162:165], v[216:219], v[18:21]
	v_mfma_f32_16x16x32_bf16 v[6:9], v[146:149], v[224:227], v[6:9]
	v_mfma_f32_16x16x32_bf16 v[2:5], v[162:165], v[224:227], v[2:5]
	v_mfma_f32_16x16x32_bf16 v[54:57], v[158:161], v[174:177], v[54:57]
	v_mfma_f32_16x16x32_bf16 v[50:53], v[166:169], v[174:177], v[50:53]
	v_mfma_f32_16x16x32_bf16 v[38:41], v[158:161], v[206:209], v[38:41]
	v_mfma_f32_16x16x32_bf16 v[34:37], v[166:169], v[206:209], v[34:37]
	v_mfma_f32_16x16x32_bf16 v[22:25], v[158:161], v[220:223], v[22:25]
	v_mfma_f32_16x16x32_bf16 v[18:21], v[166:169], v[220:223], v[18:21]
	v_mfma_f32_16x16x32_bf16 v[6:9], v[158:161], v[228:231], v[6:9]
	v_mfma_f32_16x16x32_bf16 v[2:5], v[166:169], v[228:231], v[2:5]
	s_setprio 0
	s_barrier
	v_add_u32_e32 v0, 0x18000, v156
	ds_read_b128 v[62:65], v0
	ds_read_b128 v[66:69], v0 offset:1024
	ds_read_b128 v[70:73], v0 offset:2048
	ds_read_b128 v[74:77], v0 offset:3072
	v_add_u32_e32 v0, 0x1c000, v156
	ds_read_b128 v[146:149], v0
	ds_read_b128 v[158:161], v0 offset:1024
	ds_read_b128 v[162:165], v0 offset:2048
	ds_read_b128 v[166:169], v0 offset:3072
	ds_read_b128 v[170:173], v157 offset:32768
	ds_read_b128 v[174:177], v157 offset:33792
	ds_read_b128 v[202:205], v157 offset:34816
	ds_read_b128 v[206:209], v157 offset:35840
	ds_read_b128 v[216:219], v157 offset:36864
	ds_read_b128 v[220:223], v157 offset:37888
	ds_read_b128 v[224:227], v157 offset:38912
	ds_read_b128 v[228:231], v157 offset:39936
	s_add_u32 s28, s44, s52
	s_addc_u32 s29, s45, s53
	s_mov_b32 s27, m0
	s_mov_b32 m0, s60
	s_nop 0
	global_load_lds_dwordx4 v152, s[28:29]
	s_mov_b32 m0, s61
	s_nop 0
	global_load_lds_dwordx4 v154, s[28:29]
	s_mov_b32 m0, s27
	s_waitcnt vmcnt(8)
	s_waitcnt lgkmcnt(0)
	s_barrier
	s_setprio 1
	v_mfma_f32_16x16x32_bf16 v[142:145], v[62:65], v[170:173], v[142:145]
	v_mfma_f32_16x16x32_bf16 v[138:141], v[70:73], v[170:173], v[138:141]
	v_mfma_f32_16x16x32_bf16 v[126:129], v[62:65], v[202:205], v[126:129]
	v_mfma_f32_16x16x32_bf16 v[122:125], v[70:73], v[202:205], v[122:125]
	v_mfma_f32_16x16x32_bf16 v[110:113], v[62:65], v[216:219], v[110:113]
	v_mfma_f32_16x16x32_bf16 v[106:109], v[70:73], v[216:219], v[106:109]
	v_mfma_f32_16x16x32_bf16 v[94:97], v[62:65], v[224:227], v[94:97]
	v_mfma_f32_16x16x32_bf16 v[90:93], v[70:73], v[224:227], v[90:93]
	v_mfma_f32_16x16x32_bf16 v[142:145], v[66:69], v[174:177], v[142:145]
	v_mfma_f32_16x16x32_bf16 v[138:141], v[74:77], v[174:177], v[138:141]
	v_mfma_f32_16x16x32_bf16 v[126:129], v[66:69], v[206:209], v[126:129]
	v_mfma_f32_16x16x32_bf16 v[122:125], v[74:77], v[206:209], v[122:125]
	v_mfma_f32_16x16x32_bf16 v[110:113], v[66:69], v[220:223], v[110:113]
	v_mfma_f32_16x16x32_bf16 v[106:109], v[74:77], v[220:223], v[106:109]
	v_mfma_f32_16x16x32_bf16 v[94:97], v[66:69], v[228:231], v[94:97]
	v_mfma_f32_16x16x32_bf16 v[90:93], v[74:77], v[228:231], v[90:93]
	v_mfma_f32_16x16x32_bf16 v[134:137], v[146:149], v[170:173], v[134:137]
	v_mfma_f32_16x16x32_bf16 v[130:133], v[162:165], v[170:173], v[130:133]
	v_mfma_f32_16x16x32_bf16 v[118:121], v[146:149], v[202:205], v[118:121]
	v_mfma_f32_16x16x32_bf16 v[114:117], v[162:165], v[202:205], v[114:117]
	v_mfma_f32_16x16x32_bf16 v[102:105], v[146:149], v[216:219], v[102:105]
	v_mfma_f32_16x16x32_bf16 v[98:101], v[162:165], v[216:219], v[98:101]
	v_mfma_f32_16x16x32_bf16 v[86:89], v[146:149], v[224:227], v[86:89]
	v_mfma_f32_16x16x32_bf16 v[82:85], v[162:165], v[224:227], v[82:85]
	v_mfma_f32_16x16x32_bf16 v[134:137], v[158:161], v[174:177], v[134:137]
	v_mfma_f32_16x16x32_bf16 v[130:133], v[166:169], v[174:177], v[130:133]
	v_mfma_f32_16x16x32_bf16 v[118:121], v[158:161], v[206:209], v[118:121]
	v_mfma_f32_16x16x32_bf16 v[114:117], v[166:169], v[206:209], v[114:117]
	v_mfma_f32_16x16x32_bf16 v[102:105], v[158:161], v[220:223], v[102:105]
	v_mfma_f32_16x16x32_bf16 v[98:101], v[166:169], v[220:223], v[98:101]
	v_mfma_f32_16x16x32_bf16 v[86:89], v[158:161], v[228:231], v[86:89]
	v_mfma_f32_16x16x32_bf16 v[82:85], v[166:169], v[228:231], v[82:85]
	s_setprio 0
	s_barrier
	ds_read_b128 v[170:173], v157 offset:49152
	ds_read_b128 v[174:177], v157 offset:50176
	ds_read_b128 v[202:205], v157 offset:51200
	ds_read_b128 v[206:209], v157 offset:52224
	ds_read_b128 v[216:219], v157 offset:53248
	ds_read_b128 v[220:223], v157 offset:54272
	ds_read_b128 v[224:227], v157 offset:55296
	ds_read_b128 v[228:231], v157 offset:56320
	s_add_u32 s28, s42, 0x80
	s_addc_u32 s29, s43, 0
	s_mov_b32 s27, m0
	s_mov_b32 m0, s66
	s_nop 0
	global_load_lds_dwordx4 v153, s[28:29]
	s_mov_b32 m0, s67
	s_nop 0
	global_load_lds_dwordx4 v155, s[28:29]
	s_mov_b32 m0, s27
	s_add_u32 s28, s46, 0x80
	s_addc_u32 s29, s47, 0
	s_mov_b32 s27, m0
	s_mov_b32 m0, s7
	s_nop 0
	global_load_lds_dwordx4 v153, s[28:29]
	s_mov_b32 m0, s91
	s_nop 0
	global_load_lds_dwordx4 v155, s[28:29]
	s_mov_b32 m0, s27
	s_nop 0
	s_mov_b32 s27, m0
	s_mov_b32 m0, s97
	s_nop 0
	global_load_lds_dwordx4 v152, s[40:41]
	s_mov_b32 m0, s6
	s_nop 0
	global_load_lds_dwordx4 v154, s[40:41]
	s_mov_b32 m0, s27
	s_waitcnt vmcnt(8)
	s_waitcnt lgkmcnt(0)
	s_barrier
	s_setprio 1
	v_mfma_f32_16x16x32_bf16 v[78:81], v[62:65], v[170:173], v[78:81]
	v_mfma_f32_16x16x32_bf16 v[58:61], v[70:73], v[170:173], v[58:61]
	v_mfma_f32_16x16x32_bf16 v[46:49], v[62:65], v[202:205], v[46:49]
	v_mfma_f32_16x16x32_bf16 v[42:45], v[70:73], v[202:205], v[42:45]
	v_mfma_f32_16x16x32_bf16 v[30:33], v[62:65], v[216:219], v[30:33]
	v_mfma_f32_16x16x32_bf16 v[26:29], v[70:73], v[216:219], v[26:29]
	v_mfma_f32_16x16x32_bf16 v[14:17], v[62:65], v[224:227], v[14:17]
	v_mfma_f32_16x16x32_bf16 v[10:13], v[70:73], v[224:227], v[10:13]
	v_mfma_f32_16x16x32_bf16 v[78:81], v[66:69], v[174:177], v[78:81]
	v_mfma_f32_16x16x32_bf16 v[58:61], v[74:77], v[174:177], v[58:61]
	v_mfma_f32_16x16x32_bf16 v[46:49], v[66:69], v[206:209], v[46:49]
	v_mfma_f32_16x16x32_bf16 v[42:45], v[74:77], v[206:209], v[42:45]
	v_mfma_f32_16x16x32_bf16 v[30:33], v[66:69], v[220:223], v[30:33]
	v_mfma_f32_16x16x32_bf16 v[26:29], v[74:77], v[220:223], v[26:29]
	v_mfma_f32_16x16x32_bf16 v[14:17], v[66:69], v[228:231], v[14:17]
	v_mfma_f32_16x16x32_bf16 v[10:13], v[74:77], v[228:231], v[10:13]
	v_mfma_f32_16x16x32_bf16 v[54:57], v[146:149], v[170:173], v[54:57]
	v_mfma_f32_16x16x32_bf16 v[50:53], v[162:165], v[170:173], v[50:53]
	v_mfma_f32_16x16x32_bf16 v[38:41], v[146:149], v[202:205], v[38:41]
	v_mfma_f32_16x16x32_bf16 v[34:37], v[162:165], v[202:205], v[34:37]
	v_mfma_f32_16x16x32_bf16 v[22:25], v[146:149], v[216:219], v[22:25]
	v_mfma_f32_16x16x32_bf16 v[18:21], v[162:165], v[216:219], v[18:21]
	v_mfma_f32_16x16x32_bf16 v[6:9], v[146:149], v[224:227], v[6:9]
	v_mfma_f32_16x16x32_bf16 v[2:5], v[162:165], v[224:227], v[2:5]
	v_mfma_f32_16x16x32_bf16 v[54:57], v[158:161], v[174:177], v[54:57]
	v_mfma_f32_16x16x32_bf16 v[50:53], v[166:169], v[174:177], v[50:53]
	v_mfma_f32_16x16x32_bf16 v[38:41], v[158:161], v[206:209], v[38:41]
	v_mfma_f32_16x16x32_bf16 v[34:37], v[166:169], v[206:209], v[34:37]
	v_mfma_f32_16x16x32_bf16 v[22:25], v[158:161], v[220:223], v[22:25]
	v_mfma_f32_16x16x32_bf16 v[18:21], v[166:169], v[220:223], v[18:21]
	v_mfma_f32_16x16x32_bf16 v[6:9], v[158:161], v[228:231], v[6:9]
	v_mfma_f32_16x16x32_bf16 v[2:5], v[166:169], v[228:231], v[2:5]
	s_setprio 0
	s_barrier
	s_add_i32 s26, s26, 2
	s_add_u32 s0, s0, 0x100
	s_addc_u32 s11, s11, 0
	s_add_u32 s24, s24, 0x100
	s_addc_u32 s25, s25, 0
	s_cmp_gt_u32 s26, 13
	s_cbranch_scc0 .LBB0_484
	v_readlane_b32 s24, v255, 14
	v_readlane_b32 s25, v255, 15
	s_and_b64 vcc, exec, s[24:25]
	s_cbranch_vccz .LBB0_487
	s_barrier

.LBB0_608:
	v_add_u32_e32 v135, 0x10000, v133
	ds_read_b128 v[136:139], v135
	ds_read_b128 v[140:143], v135 offset:1024
	ds_read_b128 v[144:147], v135 offset:2048
	ds_read_b128 v[148:151], v135 offset:3072
	v_add_u32_e32 v135, 0x14000, v133
	ds_read_b128 v[152:155], v135
	ds_read_b128 v[156:159], v135 offset:1024
	ds_read_b128 v[160:163], v135 offset:2048
	ds_read_b128 v[164:167], v135 offset:3072
	s_cmp_eq_u32 s81, 12
	s_cselect_b32 s58, s52, s79
	s_cselect_b32 s59, s53, s80
	s_cselect_b32 s56, s40, s11
	s_cselect_b32 s57, s41, s45
	s_add_u32 s54, s58, 0x80
	s_addc_u32 s55, s59, 0
	ds_read_b128 v[168:171], v134
	ds_read_b128 v[172:175], v134 offset:1024
	ds_read_b128 v[176:179], v134 offset:2048
	ds_read_b128 v[202:205], v134 offset:3072
	ds_read_b128 v[206:209], v134 offset:4096
	ds_read_b128 v[216:219], v134 offset:5120
	ds_read_b128 v[220:223], v134 offset:6144
	ds_read_b128 v[224:227], v134 offset:7168
	s_add_u32 s60, s79, s6
	s_addc_u32 s61, s80, s7
	s_add_u32 s60, s60, 0xffffff80
	s_addc_u32 s61, s61, -1
	s_mov_b32 s82, m0
	s_mov_b32 m0, s69
	s_nop 0
	global_load_lds_dwordx4 v0, s[60:61]
	s_mov_b32 m0, s70
	s_nop 0
	global_load_lds_dwordx4 v131, s[60:61]
	s_mov_b32 m0, s82
	s_waitcnt vmcnt(8)
	s_waitcnt lgkmcnt(0)
	s_barrier
	s_setprio 1
	v_mfma_f32_16x16x32_bf16 v[126:129], v[136:139], v[168:171], v[126:129]
	v_mfma_f32_16x16x32_bf16 v[122:125], v[144:147], v[168:171], v[122:125]
	v_mfma_f32_16x16x32_bf16 v[118:121], v[136:139], v[176:179], v[118:121]
	v_mfma_f32_16x16x32_bf16 v[114:117], v[144:147], v[176:179], v[114:117]
	v_mfma_f32_16x16x32_bf16 v[106:109], v[136:139], v[206:209], v[106:109]
	v_mfma_f32_16x16x32_bf16 v[98:101], v[144:147], v[206:209], v[98:101]
	v_mfma_f32_16x16x32_bf16 v[90:93], v[136:139], v[220:223], v[90:93]
	v_mfma_f32_16x16x32_bf16 v[82:85], v[144:147], v[220:223], v[82:85]
	v_mfma_f32_16x16x32_bf16 v[126:129], v[140:143], v[172:175], v[126:129]
	v_mfma_f32_16x16x32_bf16 v[122:125], v[148:151], v[172:175], v[122:125]
	v_mfma_f32_16x16x32_bf16 v[118:121], v[140:143], v[202:205], v[118:121]
	v_mfma_f32_16x16x32_bf16 v[114:117], v[148:151], v[202:205], v[114:117]
	v_mfma_f32_16x16x32_bf16 v[106:109], v[140:143], v[216:219], v[106:109]
	v_mfma_f32_16x16x32_bf16 v[98:101], v[148:151], v[216:219], v[98:101]
	v_mfma_f32_16x16x32_bf16 v[90:93], v[140:143], v[224:227], v[90:93]
	v_mfma_f32_16x16x32_bf16 v[82:85], v[148:151], v[224:227], v[82:85]
	v_mfma_f32_16x16x32_bf16 v[110:113], v[152:155], v[168:171], v[110:113]
	v_mfma_f32_16x16x32_bf16 v[102:105], v[160:163], v[168:171], v[102:105]
	v_mfma_f32_16x16x32_bf16 v[94:97], v[152:155], v[176:179], v[94:97]
	v_mfma_f32_16x16x32_bf16 v[86:89], v[160:163], v[176:179], v[86:89]
	v_mfma_f32_16x16x32_bf16 v[78:81], v[152:155], v[206:209], v[78:81]
	v_mfma_f32_16x16x32_bf16 v[74:77], v[160:163], v[206:209], v[74:77]
	v_mfma_f32_16x16x32_bf16 v[70:73], v[152:155], v[220:223], v[70:73]
	v_mfma_f32_16x16x32_bf16 v[66:69], v[160:163], v[220:223], v[66:69]
	v_mfma_f32_16x16x32_bf16 v[110:113], v[156:159], v[172:175], v[110:113]
	v_mfma_f32_16x16x32_bf16 v[102:105], v[164:167], v[172:175], v[102:105]
	v_mfma_f32_16x16x32_bf16 v[94:97], v[156:159], v[202:205], v[94:97]
	v_mfma_f32_16x16x32_bf16 v[86:89], v[164:167], v[202:205], v[86:89]
	v_mfma_f32_16x16x32_bf16 v[78:81], v[156:159], v[216:219], v[78:81]
	v_mfma_f32_16x16x32_bf16 v[74:77], v[164:167], v[216:219], v[74:77]
	v_mfma_f32_16x16x32_bf16 v[70:73], v[156:159], v[224:227], v[70:73]
	v_mfma_f32_16x16x32_bf16 v[66:69], v[164:167], v[224:227], v[66:69]
	s_setprio 0
	s_barrier
	ds_read_b128 v[168:171], v134 offset:16384
	ds_read_b128 v[172:175], v134 offset:17408
	ds_read_b128 v[176:179], v134 offset:18432
	ds_read_b128 v[202:205], v134 offset:19456
	ds_read_b128 v[206:209], v134 offset:20480
	ds_read_b128 v[216:219], v134 offset:21504
	ds_read_b128 v[220:223], v134 offset:22528
	ds_read_b128 v[224:227], v134 offset:23552
	s_mov_b32 s60, m0
	s_mov_b32 m0, s25
	s_nop 0
	global_load_lds_dwordx4 v130, s[56:57]
	s_mov_b32 m0, s26
	s_nop 0
	global_load_lds_dwordx4 v132, s[56:57]
	s_mov_b32 m0, s60
	s_add_u32 s60, s56, s22
	s_addc_u32 s61, s57, s23
	s_mov_b32 s82, m0
	s_mov_b32 m0, s27
	s_nop 0
	global_load_lds_dwordx4 v130, s[60:61]
	s_mov_b32 m0, s28
	s_nop 0
	global_load_lds_dwordx4 v132, s[60:61]
	s_mov_b32 m0, s82
	s_nop 0
	s_mov_b32 s82, m0
	s_mov_b32 m0, s24
	s_nop 0
	global_load_lds_dwordx4 v0, s[58:59]
	s_mov_b32 m0, s29
	s_nop 0
	global_load_lds_dwordx4 v131, s[58:59]
	s_mov_b32 m0, s82
	s_waitcnt vmcnt(8)
	s_waitcnt lgkmcnt(0)
	s_barrier
	s_setprio 1
	v_mfma_f32_16x16x32_bf16 v[62:65], v[136:139], v[168:171], v[62:65]
	v_mfma_f32_16x16x32_bf16 v[58:61], v[144:147], v[168:171], v[58:61]
	v_mfma_f32_16x16x32_bf16 v[54:57], v[136:139], v[176:179], v[54:57]
	v_mfma_f32_16x16x32_bf16 v[50:53], v[144:147], v[176:179], v[50:53]
	v_mfma_f32_16x16x32_bf16 v[38:41], v[136:139], v[206:209], v[38:41]
	v_mfma_f32_16x16x32_bf16 v[34:37], v[144:147], v[206:209], v[34:37]
	v_mfma_f32_16x16x32_bf16 v[22:25], v[136:139], v[220:223], v[22:25]
	v_mfma_f32_16x16x32_bf16 v[18:21], v[144:147], v[220:223], v[18:21]
	v_mfma_f32_16x16x32_bf16 v[62:65], v[140:143], v[172:175], v[62:65]
	v_mfma_f32_16x16x32_bf16 v[58:61], v[148:151], v[172:175], v[58:61]
	v_mfma_f32_16x16x32_bf16 v[54:57], v[140:143], v[202:205], v[54:57]
	v_mfma_f32_16x16x32_bf16 v[50:53], v[148:151], v[202:205], v[50:53]
	v_mfma_f32_16x16x32_bf16 v[38:41], v[140:143], v[216:219], v[38:41]
	v_mfma_f32_16x16x32_bf16 v[34:37], v[148:151], v[216:219], v[34:37]
	v_mfma_f32_16x16x32_bf16 v[22:25], v[140:143], v[224:227], v[22:25]
	v_mfma_f32_16x16x32_bf16 v[18:21], v[148:151], v[224:227], v[18:21]
	v_mfma_f32_16x16x32_bf16 v[46:49], v[152:155], v[168:171], v[46:49]
	v_mfma_f32_16x16x32_bf16 v[42:45], v[160:163], v[168:171], v[42:45]
	v_mfma_f32_16x16x32_bf16 v[30:33], v[152:155], v[176:179], v[30:33]
	v_mfma_f32_16x16x32_bf16 v[26:29], v[160:163], v[176:179], v[26:29]
	v_mfma_f32_16x16x32_bf16 v[14:17], v[152:155], v[206:209], v[14:17]
	v_mfma_f32_16x16x32_bf16 v[10:13], v[160:163], v[206:209], v[10:13]
	v_mfma_f32_16x16x32_bf16 v[6:9], v[152:155], v[220:223], v[6:9]
	v_mfma_f32_16x16x32_bf16 v[2:5], v[160:163], v[220:223], v[2:5]
	v_mfma_f32_16x16x32_bf16 v[46:49], v[156:159], v[172:175], v[46:49]
	v_mfma_f32_16x16x32_bf16 v[42:45], v[164:167], v[172:175], v[42:45]
	v_mfma_f32_16x16x32_bf16 v[30:33], v[156:159], v[202:205], v[30:33]
	v_mfma_f32_16x16x32_bf16 v[26:29], v[164:167], v[202:205], v[26:29]
	v_mfma_f32_16x16x32_bf16 v[14:17], v[156:159], v[216:219], v[14:17]
	v_mfma_f32_16x16x32_bf16 v[10:13], v[164:167], v[216:219], v[10:13]
	v_mfma_f32_16x16x32_bf16 v[6:9], v[156:159], v[224:227], v[6:9]
	v_mfma_f32_16x16x32_bf16 v[2:5], v[164:167], v[224:227], v[2:5]
	s_setprio 0
	s_barrier
	v_add_u32_e32 v135, 0x18000, v133
	ds_read_b128 v[136:139], v135
	ds_read_b128 v[140:143], v135 offset:1024
	ds_read_b128 v[144:147], v135 offset:2048
	ds_read_b128 v[148:151], v135 offset:3072
	v_add_u32_e32 v135, 0x1c000, v133
	ds_read_b128 v[152:155], v135
	ds_read_b128 v[156:159], v135 offset:1024
	ds_read_b128 v[160:163], v135 offset:2048
	ds_read_b128 v[164:167], v135 offset:3072
	ds_read_b128 v[168:171], v134 offset:32768
	ds_read_b128 v[172:175], v134 offset:33792
	ds_read_b128 v[176:179], v134 offset:34816
	ds_read_b128 v[202:205], v134 offset:35840
	ds_read_b128 v[206:209], v134 offset:36864
	ds_read_b128 v[216:219], v134 offset:37888
	ds_read_b128 v[220:223], v134 offset:38912
	ds_read_b128 v[224:227], v134 offset:39936
	s_add_u32 s58, s58, s6
	s_addc_u32 s59, s59, s7
	s_mov_b32 s82, m0
	s_mov_b32 m0, s30
	s_nop 0
	global_load_lds_dwordx4 v0, s[58:59]
	s_mov_b32 m0, s31
	s_nop 0
	global_load_lds_dwordx4 v131, s[58:59]
	s_mov_b32 m0, s82
	s_waitcnt vmcnt(8)
	s_waitcnt lgkmcnt(0)
	s_barrier
	s_setprio 1
	v_mfma_f32_16x16x32_bf16 v[126:129], v[136:139], v[168:171], v[126:129]
	v_mfma_f32_16x16x32_bf16 v[122:125], v[144:147], v[168:171], v[122:125]
	v_mfma_f32_16x16x32_bf16 v[118:121], v[136:139], v[176:179], v[118:121]
	v_mfma_f32_16x16x32_bf16 v[114:117], v[144:147], v[176:179], v[114:117]
	v_mfma_f32_16x16x32_bf16 v[106:109], v[136:139], v[206:209], v[106:109]
	v_mfma_f32_16x16x32_bf16 v[98:101], v[144:147], v[206:209], v[98:101]
	v_mfma_f32_16x16x32_bf16 v[90:93], v[136:139], v[220:223], v[90:93]
	v_mfma_f32_16x16x32_bf16 v[82:85], v[144:147], v[220:223], v[82:85]
	v_mfma_f32_16x16x32_bf16 v[126:129], v[140:143], v[172:175], v[126:129]
	v_mfma_f32_16x16x32_bf16 v[122:125], v[148:151], v[172:175], v[122:125]
	v_mfma_f32_16x16x32_bf16 v[118:121], v[140:143], v[202:205], v[118:121]
	v_mfma_f32_16x16x32_bf16 v[114:117], v[148:151], v[202:205], v[114:117]
	v_mfma_f32_16x16x32_bf16 v[106:109], v[140:143], v[216:219], v[106:109]
	v_mfma_f32_16x16x32_bf16 v[98:101], v[148:151], v[216:219], v[98:101]
	v_mfma_f32_16x16x32_bf16 v[90:93], v[140:143], v[224:227], v[90:93]
	v_mfma_f32_16x16x32_bf16 v[82:85], v[148:151], v[224:227], v[82:85]
	v_mfma_f32_16x16x32_bf16 v[110:113], v[152:155], v[168:171], v[110:113]
	v_mfma_f32_16x16x32_bf16 v[102:105], v[160:163], v[168:171], v[102:105]
	v_mfma_f32_16x16x32_bf16 v[94:97], v[152:155], v[176:179], v[94:97]
	v_mfma_f32_16x16x32_bf16 v[86:89], v[160:163], v[176:179], v[86:89]
	v_mfma_f32_16x16x32_bf16 v[78:81], v[152:155], v[206:209], v[78:81]
	v_mfma_f32_16x16x32_bf16 v[74:77], v[160:163], v[206:209], v[74:77]
	v_mfma_f32_16x16x32_bf16 v[70:73], v[152:155], v[220:223], v[70:73]
	v_mfma_f32_16x16x32_bf16 v[66:69], v[160:163], v[220:223], v[66:69]
	v_mfma_f32_16x16x32_bf16 v[110:113], v[156:159], v[172:175], v[110:113]
	v_mfma_f32_16x16x32_bf16 v[102:105], v[164:167], v[172:175], v[102:105]
	v_mfma_f32_16x16x32_bf16 v[94:97], v[156:159], v[202:205], v[94:97]
	v_mfma_f32_16x16x32_bf16 v[86:89], v[164:167], v[202:205], v[86:89]
	v_mfma_f32_16x16x32_bf16 v[78:81], v[156:159], v[216:219], v[78:81]
	v_mfma_f32_16x16x32_bf16 v[74:77], v[164:167], v[216:219], v[74:77]
	v_mfma_f32_16x16x32_bf16 v[70:73], v[156:159], v[224:227], v[70:73]
	v_mfma_f32_16x16x32_bf16 v[66:69], v[164:167], v[224:227], v[66:69]
	s_setprio 0
	s_barrier
	ds_read_b128 v[168:171], v134 offset:49152
	ds_read_b128 v[172:175], v134 offset:50176
	ds_read_b128 v[176:179], v134 offset:51200
	ds_read_b128 v[202:205], v134 offset:52224
	ds_read_b128 v[206:209], v134 offset:53248
	ds_read_b128 v[216:219], v134 offset:54272
	ds_read_b128 v[220:223], v134 offset:55296
	ds_read_b128 v[224:227], v134 offset:56320
	s_add_u32 s56, s56, 0x80
	s_addc_u32 s57, s57, 0
	s_mov_b32 s58, m0
	s_mov_b32 m0, s63
	s_nop 0
	global_load_lds_dwordx4 v130, s[56:57]
	s_mov_b32 m0, s64
	s_nop 0
	global_load_lds_dwordx4 v132, s[56:57]
	s_mov_b32 m0, s58
	s_add_u32 s56, s60, 0x80
	s_addc_u32 s57, s61, 0
	s_mov_b32 s58, m0
	s_mov_b32 m0, s67
	s_nop 0
	global_load_lds_dwordx4 v130, s[56:57]
	s_mov_b32 m0, s68
	s_nop 0
	global_load_lds_dwordx4 v132, s[56:57]
	s_mov_b32 m0, s58
	s_mov_b32 s56, m0
	s_mov_b32 m0, s65
	s_nop 0
	global_load_lds_dwordx4 v0, s[54:55]
	s_mov_b32 m0, s66
	s_nop 0
	global_load_lds_dwordx4 v131, s[54:55]
	s_mov_b32 m0, s56
	s_waitcnt vmcnt(8)
	s_waitcnt lgkmcnt(0)
	s_barrier
	s_setprio 1
	v_mfma_f32_16x16x32_bf16 v[62:65], v[136:139], v[168:171], v[62:65]
	v_mfma_f32_16x16x32_bf16 v[58:61], v[144:147], v[168:171], v[58:61]
	v_mfma_f32_16x16x32_bf16 v[54:57], v[136:139], v[176:179], v[54:57]
	v_mfma_f32_16x16x32_bf16 v[50:53], v[144:147], v[176:179], v[50:53]
	v_mfma_f32_16x16x32_bf16 v[38:41], v[136:139], v[206:209], v[38:41]
	v_mfma_f32_16x16x32_bf16 v[34:37], v[144:147], v[206:209], v[34:37]
	v_mfma_f32_16x16x32_bf16 v[22:25], v[136:139], v[220:223], v[22:25]
	v_mfma_f32_16x16x32_bf16 v[18:21], v[144:147], v[220:223], v[18:21]
	v_mfma_f32_16x16x32_bf16 v[62:65], v[140:143], v[172:175], v[62:65]
	v_mfma_f32_16x16x32_bf16 v[58:61], v[148:151], v[172:175], v[58:61]
	v_mfma_f32_16x16x32_bf16 v[54:57], v[140:143], v[202:205], v[54:57]
	v_mfma_f32_16x16x32_bf16 v[50:53], v[148:151], v[202:205], v[50:53]
	v_mfma_f32_16x16x32_bf16 v[38:41], v[140:143], v[216:219], v[38:41]
	v_mfma_f32_16x16x32_bf16 v[34:37], v[148:151], v[216:219], v[34:37]
	v_mfma_f32_16x16x32_bf16 v[22:25], v[140:143], v[224:227], v[22:25]
	v_mfma_f32_16x16x32_bf16 v[18:21], v[148:151], v[224:227], v[18:21]
	v_mfma_f32_16x16x32_bf16 v[46:49], v[152:155], v[168:171], v[46:49]
	v_mfma_f32_16x16x32_bf16 v[42:45], v[160:163], v[168:171], v[42:45]
	v_mfma_f32_16x16x32_bf16 v[30:33], v[152:155], v[176:179], v[30:33]
	v_mfma_f32_16x16x32_bf16 v[26:29], v[160:163], v[176:179], v[26:29]
	v_mfma_f32_16x16x32_bf16 v[14:17], v[152:155], v[206:209], v[14:17]
	v_mfma_f32_16x16x32_bf16 v[10:13], v[160:163], v[206:209], v[10:13]
	v_mfma_f32_16x16x32_bf16 v[6:9], v[152:155], v[220:223], v[6:9]
	v_mfma_f32_16x16x32_bf16 v[2:5], v[160:163], v[220:223], v[2:5]
	v_mfma_f32_16x16x32_bf16 v[46:49], v[156:159], v[172:175], v[46:49]
	v_mfma_f32_16x16x32_bf16 v[42:45], v[164:167], v[172:175], v[42:45]
	v_mfma_f32_16x16x32_bf16 v[30:33], v[156:159], v[202:205], v[30:33]
	v_mfma_f32_16x16x32_bf16 v[26:29], v[164:167], v[202:205], v[26:29]
	v_mfma_f32_16x16x32_bf16 v[14:17], v[156:159], v[216:219], v[14:17]
	v_mfma_f32_16x16x32_bf16 v[10:13], v[164:167], v[216:219], v[10:13]
	v_mfma_f32_16x16x32_bf16 v[6:9], v[156:159], v[224:227], v[6:9]
	v_mfma_f32_16x16x32_bf16 v[2:5], v[164:167], v[224:227], v[2:5]
	s_setprio 0
	s_barrier
	s_add_i32 s81, s81, 2
	s_add_u32 s11, s11, 0x100
	s_addc_u32 s45, s45, 0
	s_add_u32 s79, s79, 0x100
	s_addc_u32 s80, s80, 0
	s_cmp_gt_u32 s81, 13
	s_cbranch_scc0 .LBB0_608
	s_and_b64 vcc, exec, s[50:51]
	s_cbranch_vccz .LBB0_611
	s_barrier

.LBB0_645:
	s_add_u32 s26, s76, s42
	v_add_u32_e32 v0, 0x10000, v219
	s_addc_u32 s27, s24, s43
	ds_read_b128 v[130:133], v0
	ds_read_b128 v[134:137], v0 offset:1024
	ds_read_b128 v[138:141], v0 offset:2048
	ds_read_b128 v[142:145], v0 offset:3072
	v_add_u32_e32 v0, 0x14000, v219
	s_add_u32 s59, s54, s42
	ds_read_b128 v[146:149], v0
	ds_read_b128 v[150:153], v0 offset:1024
	ds_read_b128 v[154:157], v0 offset:2048
	ds_read_b128 v[158:161], v0 offset:3072
	s_addc_u32 s62, s55, s43
	s_add_u32 s59, s59, 0x100
	s_addc_u32 s62, s62, 0
	s_cmp_eq_u32 s25, 40
	s_cselect_b32 s66, s56, s26
	s_cselect_b32 s67, s57, s27
	s_cselect_b32 s64, s60, s59
	s_cselect_b32 s65, s61, s62
	s_add_u32 s62, s66, 0x80
	s_addc_u32 s63, s67, 0
	ds_read_b128 v[162:165], v220
	ds_read_b128 v[166:169], v220 offset:1024
	ds_read_b128 v[170:173], v220 offset:2048
	ds_read_b128 v[174:177], v220 offset:3072
	ds_read_b128 v[178:181], v220 offset:4096
	ds_read_b128 v[182:185], v220 offset:5120
	ds_read_b128 v[186:189], v220 offset:6144
	ds_read_b128 v[190:193], v220 offset:7168
	s_add_u32 s26, s10, s42
	s_addc_u32 s27, s11, s43
	s_mov_b32 s59, m0
	s_mov_b32 m0, s89
	s_nop 0
	global_load_lds_dwordx4 v215, s[26:27]
	s_mov_b32 m0, s90
	s_nop 0
	global_load_lds_dwordx4 v217, s[26:27]
	s_mov_b32 m0, s59
	s_waitcnt vmcnt(8)
	s_waitcnt lgkmcnt(0)
	s_barrier
	s_setprio 1
	v_mfma_f32_16x16x32_bf16 v[126:129], v[130:133], v[162:165], v[126:129]
	v_mfma_f32_16x16x32_bf16 v[122:125], v[138:141], v[162:165], v[122:125]
	v_mfma_f32_16x16x32_bf16 v[118:121], v[130:133], v[170:173], v[118:121]
	v_mfma_f32_16x16x32_bf16 v[114:117], v[138:141], v[170:173], v[114:117]
	v_mfma_f32_16x16x32_bf16 v[110:113], v[130:133], v[178:181], v[110:113]
	v_mfma_f32_16x16x32_bf16 v[106:109], v[138:141], v[178:181], v[106:109]
	v_mfma_f32_16x16x32_bf16 v[102:105], v[130:133], v[186:189], v[102:105]
	v_mfma_f32_16x16x32_bf16 v[98:101], v[138:141], v[186:189], v[98:101]
	v_mfma_f32_16x16x32_bf16 v[126:129], v[134:137], v[166:169], v[126:129]
	v_mfma_f32_16x16x32_bf16 v[122:125], v[142:145], v[166:169], v[122:125]
	v_mfma_f32_16x16x32_bf16 v[118:121], v[134:137], v[174:177], v[118:121]
	v_mfma_f32_16x16x32_bf16 v[114:117], v[142:145], v[174:177], v[114:117]
	v_mfma_f32_16x16x32_bf16 v[110:113], v[134:137], v[182:185], v[110:113]
	v_mfma_f32_16x16x32_bf16 v[106:109], v[142:145], v[182:185], v[106:109]
	v_mfma_f32_16x16x32_bf16 v[102:105], v[134:137], v[190:193], v[102:105]
	v_mfma_f32_16x16x32_bf16 v[98:101], v[142:145], v[190:193], v[98:101]
	v_mfma_f32_16x16x32_bf16 v[94:97], v[146:149], v[162:165], v[94:97]
	v_mfma_f32_16x16x32_bf16 v[90:93], v[154:157], v[162:165], v[90:93]
	v_mfma_f32_16x16x32_bf16 v[86:89], v[146:149], v[170:173], v[86:89]
	v_mfma_f32_16x16x32_bf16 v[82:85], v[154:157], v[170:173], v[82:85]
	v_mfma_f32_16x16x32_bf16 v[78:81], v[146:149], v[178:181], v[78:81]
	v_mfma_f32_16x16x32_bf16 v[74:77], v[154:157], v[178:181], v[74:77]
	v_mfma_f32_16x16x32_bf16 v[70:73], v[146:149], v[186:189], v[70:73]
	v_mfma_f32_16x16x32_bf16 v[66:69], v[154:157], v[186:189], v[66:69]
	v_mfma_f32_16x16x32_bf16 v[94:97], v[150:153], v[166:169], v[94:97]
	v_mfma_f32_16x16x32_bf16 v[90:93], v[158:161], v[166:169], v[90:93]
	v_mfma_f32_16x16x32_bf16 v[86:89], v[150:153], v[174:177], v[86:89]
	v_mfma_f32_16x16x32_bf16 v[82:85], v[158:161], v[174:177], v[82:85]
	v_mfma_f32_16x16x32_bf16 v[78:81], v[150:153], v[182:185], v[78:81]
	v_mfma_f32_16x16x32_bf16 v[74:77], v[158:161], v[182:185], v[74:77]
	v_mfma_f32_16x16x32_bf16 v[70:73], v[150:153], v[190:193], v[70:73]
	v_mfma_f32_16x16x32_bf16 v[66:69], v[158:161], v[190:193], v[66:69]
	s_setprio 0
	s_barrier
	ds_read_b128 v[162:165], v220 offset:16384
	ds_read_b128 v[166:169], v220 offset:17408
	ds_read_b128 v[170:173], v220 offset:18432
	ds_read_b128 v[174:177], v220 offset:19456
	ds_read_b128 v[178:181], v220 offset:20480
	ds_read_b128 v[182:185], v220 offset:21504
	ds_read_b128 v[186:189], v220 offset:22528
	ds_read_b128 v[190:193], v220 offset:23552
	s_mov_b32 s26, m0
	s_mov_b32 m0, s70
	s_nop 0
	global_load_lds_dwordx4 v216, s[64:65]
	s_mov_b32 m0, s71
	s_nop 0
	global_load_lds_dwordx4 v218, s[64:65]
	s_mov_b32 m0, s26
	s_add_u32 s68, s64, s20
	s_addc_u32 s69, s65, s21
	s_mov_b32 s26, m0
	s_mov_b32 m0, s72
	s_nop 0
	global_load_lds_dwordx4 v216, s[68:69]
	s_mov_b32 m0, s73
	s_nop 0
	global_load_lds_dwordx4 v218, s[68:69]
	s_mov_b32 m0, s26
	s_nop 0
	s_mov_b32 s26, m0
	s_mov_b32 m0, s31
	s_nop 0
	global_load_lds_dwordx4 v215, s[66:67]
	s_mov_b32 m0, s74
	s_nop 0
	global_load_lds_dwordx4 v217, s[66:67]
	s_mov_b32 m0, s26
	s_waitcnt vmcnt(8)
	s_waitcnt lgkmcnt(0)
	s_barrier
	s_setprio 1
	v_mfma_f32_16x16x32_bf16 v[62:65], v[130:133], v[162:165], v[62:65]
	v_mfma_f32_16x16x32_bf16 v[58:61], v[138:141], v[162:165], v[58:61]
	v_mfma_f32_16x16x32_bf16 v[54:57], v[130:133], v[170:173], v[54:57]
	v_mfma_f32_16x16x32_bf16 v[50:53], v[138:141], v[170:173], v[50:53]
	v_mfma_f32_16x16x32_bf16 v[46:49], v[130:133], v[178:181], v[46:49]
	v_mfma_f32_16x16x32_bf16 v[42:45], v[138:141], v[178:181], v[42:45]
	v_mfma_f32_16x16x32_bf16 v[38:41], v[130:133], v[186:189], v[38:41]
	v_mfma_f32_16x16x32_bf16 v[34:37], v[138:141], v[186:189], v[34:37]
	v_mfma_f32_16x16x32_bf16 v[62:65], v[134:137], v[166:169], v[62:65]
	v_mfma_f32_16x16x32_bf16 v[58:61], v[142:145], v[166:169], v[58:61]
	v_mfma_f32_16x16x32_bf16 v[54:57], v[134:137], v[174:177], v[54:57]
	v_mfma_f32_16x16x32_bf16 v[50:53], v[142:145], v[174:177], v[50:53]
	v_mfma_f32_16x16x32_bf16 v[46:49], v[134:137], v[182:185], v[46:49]
	v_mfma_f32_16x16x32_bf16 v[42:45], v[142:145], v[182:185], v[42:45]
	v_mfma_f32_16x16x32_bf16 v[38:41], v[134:137], v[190:193], v[38:41]
	v_mfma_f32_16x16x32_bf16 v[34:37], v[142:145], v[190:193], v[34:37]
	v_mfma_f32_16x16x32_bf16 v[30:33], v[146:149], v[162:165], v[30:33]
	v_mfma_f32_16x16x32_bf16 v[26:29], v[154:157], v[162:165], v[26:29]
	v_mfma_f32_16x16x32_bf16 v[22:25], v[146:149], v[170:173], v[22:25]
	v_mfma_f32_16x16x32_bf16 v[18:21], v[154:157], v[170:173], v[18:21]
	v_mfma_f32_16x16x32_bf16 v[14:17], v[146:149], v[178:181], v[14:17]
	v_mfma_f32_16x16x32_bf16 v[10:13], v[154:157], v[178:181], v[10:13]
	v_mfma_f32_16x16x32_bf16 v[6:9], v[146:149], v[186:189], v[6:9]
	v_mfma_f32_16x16x32_bf16 v[2:5], v[154:157], v[186:189], v[2:5]
	v_mfma_f32_16x16x32_bf16 v[30:33], v[150:153], v[166:169], v[30:33]
	v_mfma_f32_16x16x32_bf16 v[26:29], v[158:161], v[166:169], v[26:29]
	v_mfma_f32_16x16x32_bf16 v[22:25], v[150:153], v[174:177], v[22:25]
	v_mfma_f32_16x16x32_bf16 v[18:21], v[158:161], v[174:177], v[18:21]
	v_mfma_f32_16x16x32_bf16 v[14:17], v[150:153], v[182:185], v[14:17]
	v_mfma_f32_16x16x32_bf16 v[10:13], v[158:161], v[182:185], v[10:13]
	v_mfma_f32_16x16x32_bf16 v[6:9], v[150:153], v[190:193], v[6:9]
	v_mfma_f32_16x16x32_bf16 v[2:5], v[158:161], v[190:193], v[2:5]
	s_setprio 0
	s_barrier
	v_add_u32_e32 v0, 0x18000, v219
	ds_read_b128 v[130:133], v0
	ds_read_b128 v[134:137], v0 offset:1024
	ds_read_b128 v[138:141], v0 offset:2048
	ds_read_b128 v[142:145], v0 offset:3072
	v_add_u32_e32 v0, 0x1c000, v219
	ds_read_b128 v[146:149], v0
	ds_read_b128 v[150:153], v0 offset:1024
	ds_read_b128 v[154:157], v0 offset:2048
	ds_read_b128 v[158:161], v0 offset:3072
	ds_read_b128 v[162:165], v220 offset:32768
	ds_read_b128 v[166:169], v220 offset:33792
	ds_read_b128 v[170:173], v220 offset:34816
	ds_read_b128 v[174:177], v220 offset:35840
	ds_read_b128 v[178:181], v220 offset:36864
	ds_read_b128 v[182:185], v220 offset:37888
	ds_read_b128 v[186:189], v220 offset:38912
	ds_read_b128 v[190:193], v220 offset:39936
	s_add_u32 s26, s66, s4
	s_addc_u32 s27, s67, s5
	s_mov_b32 s59, m0
	s_mov_b32 m0, s75
	s_nop 0
	global_load_lds_dwordx4 v215, s[26:27]
	s_mov_b32 m0, s79
	s_nop 0
	global_load_lds_dwordx4 v217, s[26:27]
	s_mov_b32 m0, s59
	s_waitcnt vmcnt(8)
	s_waitcnt lgkmcnt(0)
	s_barrier
	s_setprio 1
	v_mfma_f32_16x16x32_bf16 v[126:129], v[130:133], v[162:165], v[126:129]
	v_mfma_f32_16x16x32_bf16 v[122:125], v[138:141], v[162:165], v[122:125]
	v_mfma_f32_16x16x32_bf16 v[118:121], v[130:133], v[170:173], v[118:121]
	v_mfma_f32_16x16x32_bf16 v[114:117], v[138:141], v[170:173], v[114:117]
	v_mfma_f32_16x16x32_bf16 v[110:113], v[130:133], v[178:181], v[110:113]
	v_mfma_f32_16x16x32_bf16 v[106:109], v[138:141], v[178:181], v[106:109]
	v_mfma_f32_16x16x32_bf16 v[102:105], v[130:133], v[186:189], v[102:105]
	v_mfma_f32_16x16x32_bf16 v[98:101], v[138:141], v[186:189], v[98:101]
	v_mfma_f32_16x16x32_bf16 v[126:129], v[134:137], v[166:169], v[126:129]
	v_mfma_f32_16x16x32_bf16 v[122:125], v[142:145], v[166:169], v[122:125]
	v_mfma_f32_16x16x32_bf16 v[118:121], v[134:137], v[174:177], v[118:121]
	v_mfma_f32_16x16x32_bf16 v[114:117], v[142:145], v[174:177], v[114:117]
	v_mfma_f32_16x16x32_bf16 v[110:113], v[134:137], v[182:185], v[110:113]
	v_mfma_f32_16x16x32_bf16 v[106:109], v[142:145], v[182:185], v[106:109]
	v_mfma_f32_16x16x32_bf16 v[102:105], v[134:137], v[190:193], v[102:105]
	v_mfma_f32_16x16x32_bf16 v[98:101], v[142:145], v[190:193], v[98:101]
	v_mfma_f32_16x16x32_bf16 v[94:97], v[146:149], v[162:165], v[94:97]
	v_mfma_f32_16x16x32_bf16 v[90:93], v[154:157], v[162:165], v[90:93]
	v_mfma_f32_16x16x32_bf16 v[86:89], v[146:149], v[170:173], v[86:89]
	v_mfma_f32_16x16x32_bf16 v[82:85], v[154:157], v[170:173], v[82:85]
	v_mfma_f32_16x16x32_bf16 v[78:81], v[146:149], v[178:181], v[78:81]
	v_mfma_f32_16x16x32_bf16 v[74:77], v[154:157], v[178:181], v[74:77]
	v_mfma_f32_16x16x32_bf16 v[70:73], v[146:149], v[186:189], v[70:73]
	v_mfma_f32_16x16x32_bf16 v[66:69], v[154:157], v[186:189], v[66:69]
	v_mfma_f32_16x16x32_bf16 v[94:97], v[150:153], v[166:169], v[94:97]
	v_mfma_f32_16x16x32_bf16 v[90:93], v[158:161], v[166:169], v[90:93]
	v_mfma_f32_16x16x32_bf16 v[86:89], v[150:153], v[174:177], v[86:89]
	v_mfma_f32_16x16x32_bf16 v[82:85], v[158:161], v[174:177], v[82:85]
	v_mfma_f32_16x16x32_bf16 v[78:81], v[150:153], v[182:185], v[78:81]
	v_mfma_f32_16x16x32_bf16 v[74:77], v[158:161], v[182:185], v[74:77]
	v_mfma_f32_16x16x32_bf16 v[70:73], v[150:153], v[190:193], v[70:73]
	v_mfma_f32_16x16x32_bf16 v[66:69], v[158:161], v[190:193], v[66:69]
	s_setprio 0
	s_barrier
	ds_read_b128 v[162:165], v220 offset:49152
	ds_read_b128 v[166:169], v220 offset:50176
	ds_read_b128 v[170:173], v220 offset:51200
	ds_read_b128 v[174:177], v220 offset:52224
	ds_read_b128 v[178:181], v220 offset:53248
	ds_read_b128 v[182:185], v220 offset:54272
	ds_read_b128 v[186:189], v220 offset:55296
	ds_read_b128 v[190:193], v220 offset:56320
	s_add_u32 s26, s64, 0x80
	s_addc_u32 s27, s65, 0
	s_mov_b32 s59, m0
	s_mov_b32 m0, s83
	s_nop 0
	global_load_lds_dwordx4 v216, s[26:27]
	s_mov_b32 m0, s84
	s_nop 0
	global_load_lds_dwordx4 v218, s[26:27]
	s_mov_b32 m0, s59
	s_add_u32 s26, s68, 0x80
	s_addc_u32 s27, s69, 0
	s_mov_b32 s59, m0
	s_mov_b32 m0, s87
	s_nop 0
	global_load_lds_dwordx4 v216, s[26:27]
	s_mov_b32 m0, s88
	s_nop 0
	global_load_lds_dwordx4 v218, s[26:27]
	s_mov_b32 m0, s59
	s_mov_b32 s26, m0
	s_mov_b32 m0, s85
	s_nop 0
	global_load_lds_dwordx4 v215, s[62:63]
	s_mov_b32 m0, s86
	s_nop 0
	global_load_lds_dwordx4 v217, s[62:63]
	s_mov_b32 m0, s26
	s_waitcnt vmcnt(8)
	s_waitcnt lgkmcnt(0)
	s_barrier
	s_setprio 1
	v_mfma_f32_16x16x32_bf16 v[62:65], v[130:133], v[162:165], v[62:65]
	v_mfma_f32_16x16x32_bf16 v[58:61], v[138:141], v[162:165], v[58:61]
	v_mfma_f32_16x16x32_bf16 v[54:57], v[130:133], v[170:173], v[54:57]
	v_mfma_f32_16x16x32_bf16 v[50:53], v[138:141], v[170:173], v[50:53]
	v_mfma_f32_16x16x32_bf16 v[46:49], v[130:133], v[178:181], v[46:49]
	v_mfma_f32_16x16x32_bf16 v[42:45], v[138:141], v[178:181], v[42:45]
	v_mfma_f32_16x16x32_bf16 v[38:41], v[130:133], v[186:189], v[38:41]
	v_mfma_f32_16x16x32_bf16 v[34:37], v[138:141], v[186:189], v[34:37]
	v_mfma_f32_16x16x32_bf16 v[62:65], v[134:137], v[166:169], v[62:65]
	v_mfma_f32_16x16x32_bf16 v[58:61], v[142:145], v[166:169], v[58:61]
	v_mfma_f32_16x16x32_bf16 v[54:57], v[134:137], v[174:177], v[54:57]
	v_mfma_f32_16x16x32_bf16 v[50:53], v[142:145], v[174:177], v[50:53]
	v_mfma_f32_16x16x32_bf16 v[46:49], v[134:137], v[182:185], v[46:49]
	v_mfma_f32_16x16x32_bf16 v[42:45], v[142:145], v[182:185], v[42:45]
	v_mfma_f32_16x16x32_bf16 v[38:41], v[134:137], v[190:193], v[38:41]
	v_mfma_f32_16x16x32_bf16 v[34:37], v[142:145], v[190:193], v[34:37]
	v_mfma_f32_16x16x32_bf16 v[30:33], v[146:149], v[162:165], v[30:33]
	v_mfma_f32_16x16x32_bf16 v[26:29], v[154:157], v[162:165], v[26:29]
	v_mfma_f32_16x16x32_bf16 v[22:25], v[146:149], v[170:173], v[22:25]
	v_mfma_f32_16x16x32_bf16 v[18:21], v[154:157], v[170:173], v[18:21]
	v_mfma_f32_16x16x32_bf16 v[14:17], v[146:149], v[178:181], v[14:17]
	v_mfma_f32_16x16x32_bf16 v[10:13], v[154:157], v[178:181], v[10:13]
	v_mfma_f32_16x16x32_bf16 v[6:9], v[146:149], v[186:189], v[6:9]
	v_mfma_f32_16x16x32_bf16 v[2:5], v[154:157], v[186:189], v[2:5]
	v_mfma_f32_16x16x32_bf16 v[30:33], v[150:153], v[166:169], v[30:33]
	v_mfma_f32_16x16x32_bf16 v[26:29], v[158:161], v[166:169], v[26:29]
	v_mfma_f32_16x16x32_bf16 v[22:25], v[150:153], v[174:177], v[22:25]
	v_mfma_f32_16x16x32_bf16 v[18:21], v[158:161], v[174:177], v[18:21]
	v_mfma_f32_16x16x32_bf16 v[14:17], v[150:153], v[182:185], v[14:17]
	v_mfma_f32_16x16x32_bf16 v[10:13], v[158:161], v[182:185], v[10:13]
	v_mfma_f32_16x16x32_bf16 v[6:9], v[150:153], v[190:193], v[6:9]
	v_mfma_f32_16x16x32_bf16 v[2:5], v[158:161], v[190:193], v[2:5]
	s_setprio 0
	s_barrier
	s_add_i32 s25, s25, 2
	s_add_u32 s42, s42, 0x100
	s_addc_u32 s43, s43, 0
	s_cmp_gt_u32 s25, 41
	s_cbranch_scc0 .LBB0_645
	s_and_b64 vcc, exec, s[50:51]
	s_cbranch_vccz .LBB0_648
	s_barrier
